# EpiRetIn: the four rotation-table loads of a row block issued together with counted vmcnt waits; slab pre-step sums 4 pieces per iteration
# baseline (speedup 1.0000x reference)
.LBB0_1939:
	s_or_b64 exec, exec, s[38:39]
	v_ashrrev_i32_e32 v155, 31, v154
	v_lshlrev_b64 v[154:155], 7, v[154:155]
	v_cndmask_b32_e64 v155, 0, v155, s[46:47]
	v_cndmask_b32_e64 v154, v234, v154, s[46:47]
	v_or_b32_e32 v160, v154, v136
	v_mov_b32_e32 v161, v155
	v_lshl_add_u64 v[160:161], v[160:161], 3, s[78:79]
	global_load_dwordx4 v[168:171], v[160:161], off
	v_or_b32_e32 v188, v154, v138
	v_mov_b32_e32 v189, v155
	v_lshl_add_u64 v[188:189], v[188:189], 3, s[78:79]
	global_load_dwordx4 v[176:179], v[188:189], off
	v_or_b32_e32 v188, v154, v140
	v_mov_b32_e32 v189, v155
	v_lshl_add_u64 v[188:189], v[188:189], 3, s[78:79]
	global_load_dwordx4 v[180:183], v[188:189], off
	v_or_b32_e32 v188, v154, v142
	v_mov_b32_e32 v189, v155
	v_lshl_add_u64 v[188:189], v[188:189], 3, s[78:79]
	global_load_dwordx4 v[184:187], v[188:189], off
	v_mov_b32_e32 v80, v129
	s_mov_b32 s6, 0x3d800000
	v_ashrrev_i32_e32 v149, 31, v148
	v_lshlrev_b64 v[158:159], 11, v[148:149]
	v_lshl_or_b32 v149, v167, 10, s59
	v_ashrrev_i32_e32 v153, 31, v152
	s_waitcnt vmcnt(3)
	v_pk_mul_f32 v[160:161], v[126:127], v[168:169] op_sel:[1,1] op_sel_hi:[1,0]
	s_nop 0
	v_pk_fma_f32 v[172:173], v[126:127], v[168:169], v[160:161] op_sel_hi:[0,1,1] neg_lo:[0,0,1] neg_hi:[0,0,1]
	v_pk_fma_f32 v[126:127], v[126:127], v[168:169], v[160:161] op_sel_hi:[0,1,1]
	v_pk_mul_f32 v[160:161], v[80:81], v[170:171] op_sel:[0,1] op_sel_hi:[0,0]
	v_pk_fma_f32 v[168:169], v[128:129], v[170:171], v[160:161] op_sel_hi:[0,1,1] neg_lo:[0,0,1] neg_hi:[0,0,1]
	v_pk_fma_f32 v[160:161], v[128:129], v[170:171], v[160:161] op_sel_hi:[0,1,1]
	v_mov_b32_e32 v169, v161
	v_mov_b32_e32 v173, v127
	v_pk_mul_f32 v[170:171], v[168:169], s[6:7] op_sel_hi:[1,0]
	v_pk_mul_f32 v[174:175], v[172:173], s[6:7] op_sel_hi:[1,0]
	s_and_b64 s[6:7], s[44:45], exec
	v_readlane_b32 s6, v252, 32
	v_readlane_b32 s7, v252, 33
	s_cselect_b32 s7, s7, s29
	s_cselect_b32 s6, s6, s28
	v_cndmask_b32_e64 v157, v127, v175, s[44:45]
	v_lshl_add_u64 v[126:127], s[6:7], 0, v[158:159]
	s_lshl_b32 s6, s59, 1
	s_mov_b32 s7, s93
	v_lshl_add_u64 v[126:127], v[126:127], 0, s[6:7]
	v_lshlrev_b32_e32 v80, 1, v134
	v_cndmask_b32_e64 v129, v168, v170, s[44:45]
	v_cndmask_b32_e64 v128, v161, v171, s[44:45]
	v_cndmask_b32_e64 v167, v172, v174, s[44:45]
	v_lshl_add_u64 v[126:127], v[126:127], 0, v[80:81]
	v_cvt_pk_bf16_f32 v160, v167, v157
	v_cvt_pk_bf16_f32 v161, v129, v128
	global_store_dwordx2 v[126:127], v[160:161], off
	s_and_saveexec_b64 s[46:47], s[4:5]
	s_cbranch_execz .LBB0_1941
	v_readlane_b32 s6, v250, 37
	v_readlane_b32 s7, v250, 38
	v_or_b32_e32 v80, v149, v134
	s_nop 0
	v_mov_b64_e32 v[158:159], s[6:7]
	v_mad_i64_i32 v[158:159], s[6:7], v80, s9, v[158:159]
	v_mul_f32_e32 v80, v151, v167
	v_bfe_u32 v160, v80, 16, 1
	v_lshl_add_u64 v[158:159], v[152:153], 1, v[158:159]
	v_add3_u32 v80, v80, v160, s89
	global_store_short_d16_hi v[158:159], v80, off
	v_mul_f32_e32 v80, v151, v157
	v_bfe_u32 v157, v80, 16, 1
	v_add_co_u32_e32 v160, vcc, 0x1000, v158
	v_add3_u32 v80, v80, v157, s89
	s_nop 0
	v_addc_co_u32_e32 v161, vcc, 0, v159, vcc
	global_store_short_d16_hi v[160:161], v80, off offset:32
	v_mul_f32_e32 v80, v151, v129
	v_bfe_u32 v129, v80, 16, 1
	v_add_co_u32_e32 v160, vcc, 0x2000, v158
	v_add3_u32 v80, v80, v129, s89
	s_nop 0
	v_addc_co_u32_e32 v161, vcc, 0, v159, vcc
	global_store_short_d16_hi v[160:161], v80, off offset:64
	v_mul_f32_e32 v80, v151, v128
	v_bfe_u32 v128, v80, 16, 1
	v_add3_u32 v80, v80, v128, s89
	v_add_co_u32_e32 v128, vcc, 0x3000, v158
	s_nop 1
	v_addc_co_u32_e32 v129, vcc, 0, v159, vcc
	global_store_short_d16_hi v[128:129], v80, off offset:96
.LBB0_1941:
	s_or_b64 exec, exec, s[46:47]
	v_or_b32_e32 v128, v154, v138
	v_mov_b32_e32 v129, v155
	v_lshl_add_u64 v[128:129], v[128:129], 3, s[78:79]
	s_and_b64 s[38:39], exec, s[4:5]
	s_cbranch_scc0 .Lrope_q_0_1
	s_waitcnt vmcnt(7)
	s_branch .Lrope_w_0_1
.Lrope_q_0_1:
	s_waitcnt vmcnt(3)
.Lrope_w_0_1:
	v_mov_b64_e32 v[168:169], v[176:177]
	v_mov_b64_e32 v[170:171], v[178:179]
	v_mov_b32_e32 v80, v125
	s_mov_b32 s6, 0x3d800000
	s_nop 0
	v_pk_mul_f32 v[128:129], v[122:123], v[168:169] op_sel:[1,1] op_sel_hi:[1,0]
	s_nop 0
	v_pk_fma_f32 v[158:159], v[122:123], v[168:169], v[128:129] op_sel_hi:[0,1,1] neg_lo:[0,0,1] neg_hi:[0,0,1]
	v_pk_fma_f32 v[122:123], v[122:123], v[168:169], v[128:129] op_sel_hi:[0,1,1]
	v_pk_mul_f32 v[128:129], v[80:81], v[170:171] op_sel:[0,1] op_sel_hi:[0,0]
	v_pk_fma_f32 v[160:161], v[124:125], v[170:171], v[128:129] op_sel_hi:[0,1,1] neg_lo:[0,0,1] neg_hi:[0,0,1]
	v_pk_fma_f32 v[124:125], v[124:125], v[170:171], v[128:129] op_sel_hi:[0,1,1]
	v_mov_b32_e32 v161, v125
	v_mov_b32_e32 v159, v123
	v_pk_mul_f32 v[128:129], v[160:161], s[6:7] op_sel_hi:[1,0]
	v_pk_mul_f32 v[168:169], v[158:159], s[6:7] op_sel_hi:[1,0]
	v_cndmask_b32_e64 v122, v160, v128, s[44:45]
	v_cndmask_b32_e64 v80, v125, v129, s[44:45]
	v_cndmask_b32_e64 v124, v158, v168, s[44:45]
	v_cndmask_b32_e64 v123, v123, v169, s[44:45]
	v_cvt_pk_bf16_f32 v128, v124, v123
	v_cvt_pk_bf16_f32 v129, v122, v80
	global_store_dwordx2 v[126:127], v[128:129], off offset:32
	s_and_saveexec_b64 s[46:47], s[4:5]
	s_cbranch_execz .LBB0_1943
	v_readlane_b32 s6, v250, 37
	v_readlane_b32 s7, v250, 38
	v_or_b32_e32 v125, v149, v141
	v_mul_f32_e32 v124, v151, v124
	v_mov_b64_e32 v[128:129], s[6:7]
	v_mad_i64_i32 v[128:129], s[6:7], v125, s9, v[128:129]
	v_bfe_u32 v125, v124, 16, 1
	v_lshl_add_u64 v[128:129], v[152:153], 1, v[128:129]
	v_add3_u32 v124, v124, v125, s89
	v_mul_f32_e32 v123, v151, v123
	global_store_short_d16_hi v[128:129], v124, off
	v_bfe_u32 v124, v123, 16, 1
	v_add3_u32 v123, v123, v124, s89
	v_add_co_u32_e32 v124, vcc, 0x1000, v128
	v_mul_f32_e32 v122, v151, v122
	s_nop 0
	v_addc_co_u32_e32 v125, vcc, 0, v129, vcc
	global_store_short_d16_hi v[124:125], v123, off offset:32
	v_bfe_u32 v123, v122, 16, 1
	v_add3_u32 v124, v122, v123, s89
	v_add_co_u32_e32 v122, vcc, 0x2000, v128
	v_mul_f32_e32 v80, v151, v80
	s_nop 0
	v_addc_co_u32_e32 v123, vcc, 0, v129, vcc
	global_store_short_d16_hi v[122:123], v124, off offset:64
	v_bfe_u32 v122, v80, 16, 1
	v_add3_u32 v80, v80, v122, s89
	v_add_co_u32_e32 v122, vcc, 0x3000, v128
	s_nop 1
	v_addc_co_u32_e32 v123, vcc, 0, v129, vcc
	global_store_short_d16_hi v[122:123], v80, off offset:96
.LBB0_1943:
	s_or_b64 exec, exec, s[46:47]
	v_or_b32_e32 v122, v154, v140
	v_mov_b32_e32 v123, v155
	v_lshl_add_u64 v[122:123], v[122:123], 3, s[78:79]
	s_and_b64 s[38:39], exec, s[4:5]
	s_cbranch_scc0 .Lrope_q_0_2
	s_waitcnt vmcnt(11)
	s_branch .Lrope_w_0_2

.Lrope_w_0_2:
	v_mov_b64_e32 v[122:123], v[180:181]
	v_mov_b64_e32 v[124:125], v[182:183]
	v_mov_b32_e32 v80, v121
	s_mov_b32 s6, 0x3d800000
	s_nop 0
	v_pk_mul_f32 v[128:129], v[118:119], v[122:123] op_sel:[1,1] op_sel_hi:[1,0]
	s_nop 0
	v_pk_fma_f32 v[158:159], v[118:119], v[122:123], v[128:129] op_sel_hi:[0,1,1] neg_lo:[0,0,1] neg_hi:[0,0,1]
	v_pk_fma_f32 v[118:119], v[118:119], v[122:123], v[128:129] op_sel_hi:[0,1,1]
	v_pk_mul_f32 v[122:123], v[80:81], v[124:125] op_sel:[0,1] op_sel_hi:[0,0]
	v_pk_fma_f32 v[128:129], v[120:121], v[124:125], v[122:123] op_sel_hi:[0,1,1] neg_lo:[0,0,1] neg_hi:[0,0,1]
	v_pk_fma_f32 v[120:121], v[120:121], v[124:125], v[122:123] op_sel_hi:[0,1,1]
	v_mov_b32_e32 v129, v121
	v_mov_b32_e32 v159, v119
	v_pk_mul_f32 v[122:123], v[128:129], s[6:7] op_sel_hi:[1,0]
	v_pk_mul_f32 v[124:125], v[158:159], s[6:7] op_sel_hi:[1,0]
	v_cndmask_b32_e64 v118, v128, v122, s[44:45]
	v_cndmask_b32_e64 v80, v121, v123, s[44:45]
	v_cndmask_b32_e64 v120, v158, v124, s[44:45]
	v_cndmask_b32_e64 v119, v119, v125, s[44:45]
	v_cvt_pk_bf16_f32 v122, v120, v119
	v_cvt_pk_bf16_f32 v123, v118, v80
	global_store_dwordx2 v[126:127], v[122:123], off offset:256
	s_and_saveexec_b64 s[46:47], s[4:5]
	s_cbranch_execz .LBB0_1945
	v_readlane_b32 s6, v250, 37
	v_readlane_b32 s7, v250, 38
	v_or_b32_e32 v121, v149, v143
	v_mul_f32_e32 v120, v151, v120
	v_mov_b64_e32 v[122:123], s[6:7]
	v_mad_i64_i32 v[122:123], s[6:7], v121, s9, v[122:123]
	v_bfe_u32 v121, v120, 16, 1
	v_lshl_add_u64 v[122:123], v[152:153], 1, v[122:123]
	v_add3_u32 v120, v120, v121, s89
	v_mul_f32_e32 v119, v151, v119
	global_store_short_d16_hi v[122:123], v120, off
	v_bfe_u32 v120, v119, 16, 1
	v_add3_u32 v119, v119, v120, s89
	v_add_co_u32_e32 v120, vcc, 0x1000, v122
	v_mul_f32_e32 v118, v151, v118
	s_nop 0
	v_addc_co_u32_e32 v121, vcc, 0, v123, vcc
	global_store_short_d16_hi v[120:121], v119, off offset:32
	v_bfe_u32 v119, v118, 16, 1
	v_add3_u32 v120, v118, v119, s89
	v_add_co_u32_e32 v118, vcc, 0x2000, v122
	v_mul_f32_e32 v80, v151, v80
	s_nop 0
	v_addc_co_u32_e32 v119, vcc, 0, v123, vcc
	global_store_short_d16_hi v[118:119], v120, off offset:64
	v_bfe_u32 v118, v80, 16, 1
	v_add3_u32 v80, v80, v118, s89
	v_add_co_u32_e32 v118, vcc, 0x3000, v122
	s_nop 1
	v_addc_co_u32_e32 v119, vcc, 0, v123, vcc
	global_store_short_d16_hi v[118:119], v80, off offset:96
.LBB0_1945:
	s_or_b64 exec, exec, s[46:47]
	v_or_b32_e32 v154, v154, v142
	v_lshl_add_u64 v[118:119], v[154:155], 3, s[78:79]
	s_and_b64 s[38:39], exec, s[4:5]
	s_cbranch_scc0 .Lrope_q_0_3
	s_waitcnt vmcnt(15)
	s_branch .Lrope_w_0_3

.Lrope_w_0_3:
	v_mov_b64_e32 v[118:119], v[184:185]
	v_mov_b64_e32 v[120:121], v[186:187]
	v_mov_b32_e32 v80, v117
	s_mov_b32 s6, 0x3d800000
	s_nop 0
	v_pk_mul_f32 v[122:123], v[114:115], v[118:119] op_sel:[1,1] op_sel_hi:[1,0]
	s_nop 0
	v_pk_fma_f32 v[124:125], v[114:115], v[118:119], v[122:123] op_sel_hi:[0,1,1] neg_lo:[0,0,1] neg_hi:[0,0,1]
	v_pk_fma_f32 v[114:115], v[114:115], v[118:119], v[122:123] op_sel_hi:[0,1,1]
	v_pk_mul_f32 v[118:119], v[80:81], v[120:121] op_sel:[0,1] op_sel_hi:[0,0]
	v_pk_fma_f32 v[122:123], v[116:117], v[120:121], v[118:119] op_sel_hi:[0,1,1] neg_lo:[0,0,1] neg_hi:[0,0,1]
	v_pk_fma_f32 v[116:117], v[116:117], v[120:121], v[118:119] op_sel_hi:[0,1,1]
	v_mov_b32_e32 v123, v117
	v_mov_b32_e32 v125, v115
	v_pk_mul_f32 v[118:119], v[122:123], s[6:7] op_sel_hi:[1,0]
	v_pk_mul_f32 v[120:121], v[124:125], s[6:7] op_sel_hi:[1,0]
	v_cndmask_b32_e64 v114, v122, v118, s[44:45]
	v_cndmask_b32_e64 v80, v117, v119, s[44:45]
	v_cndmask_b32_e64 v116, v124, v120, s[44:45]
	v_cndmask_b32_e64 v115, v115, v121, s[44:45]
	v_cvt_pk_bf16_f32 v118, v116, v115
	v_cvt_pk_bf16_f32 v119, v114, v80
	global_store_dwordx2 v[126:127], v[118:119], off offset:288
	s_and_saveexec_b64 s[46:47], s[4:5]
	s_cbranch_execz .LBB0_1947
	v_readlane_b32 s4, v250, 37
	v_readlane_b32 s5, v250, 38
	v_or_b32_e32 v117, v149, v164
	v_mul_f32_e32 v116, v151, v116
	v_mov_b64_e32 v[118:119], s[4:5]
	v_mad_i64_i32 v[118:119], s[4:5], v117, s9, v[118:119]
	v_bfe_u32 v117, v116, 16, 1
	v_lshl_add_u64 v[118:119], v[152:153], 1, v[118:119]
	v_add3_u32 v116, v116, v117, s89
	v_mul_f32_e32 v115, v151, v115
	global_store_short_d16_hi v[118:119], v116, off
	v_bfe_u32 v116, v115, 16, 1
	v_add3_u32 v115, v115, v116, s89
	v_add_co_u32_e32 v116, vcc, 0x1000, v118
	v_mul_f32_e32 v114, v151, v114
	s_nop 0
	v_addc_co_u32_e32 v117, vcc, 0, v119, vcc
	global_store_short_d16_hi v[116:117], v115, off offset:32
	v_bfe_u32 v115, v114, 16, 1
	v_add3_u32 v116, v114, v115, s89
	v_add_co_u32_e32 v114, vcc, 0x2000, v118
	v_mul_f32_e32 v80, v151, v80
	s_nop 0
	v_addc_co_u32_e32 v115, vcc, 0, v119, vcc
	global_store_short_d16_hi v[114:115], v116, off offset:64
	v_bfe_u32 v114, v80, 16, 1
	v_add3_u32 v80, v80, v114, s89
	v_add_co_u32_e32 v114, vcc, 0x3000, v118
	s_nop 1
	v_addc_co_u32_e32 v115, vcc, 0, v119, vcc
	global_store_short_d16_hi v[114:115], v80, off offset:96

.LBB0_1967:
	s_or_b64 exec, exec, s[12:13]
	v_ashrrev_i32_e32 v119, 31, v118
	v_lshlrev_b64 v[118:119], 7, v[118:119]
	v_cndmask_b32_e64 v119, 0, v119, s[50:51]
	v_cndmask_b32_e64 v118, v234, v118, s[50:51]
	v_ashrrev_i32_e32 v117, 31, v116
	v_lshlrev_b64 v[126:127], 11, v[116:117]
	v_lshl_or_b32 v116, v122, 10, s59
	v_or_b32_e32 v122, v118, v136
	v_mov_b32_e32 v123, v119
	v_lshl_add_u64 v[122:123], v[122:123], 3, s[78:79]
	global_load_dwordx4 v[122:125], v[122:123], off
	v_or_b32_e32 v188, v118, v138
	v_mov_b32_e32 v189, v119
	v_lshl_add_u64 v[188:189], v[188:189], 3, s[78:79]
	global_load_dwordx4 v[176:179], v[188:189], off
	v_or_b32_e32 v188, v118, v140
	v_mov_b32_e32 v189, v119
	v_lshl_add_u64 v[188:189], v[188:189], 3, s[78:79]
	global_load_dwordx4 v[180:183], v[188:189], off
	v_or_b32_e32 v188, v118, v142
	v_mov_b32_e32 v189, v119
	v_lshl_add_u64 v[188:189], v[188:189], 3, s[78:79]
	global_load_dwordx4 v[184:187], v[188:189], off
	v_mov_b32_e32 v80, v113
	s_mov_b32 s6, 0x3d800000
	v_ashrrev_i32_e32 v115, 31, v114
	s_waitcnt vmcnt(3)
	v_pk_mul_f32 v[128:129], v[110:111], v[122:123] op_sel:[1,1] op_sel_hi:[1,0]
	s_nop 0
	v_pk_fma_f32 v[152:153], v[110:111], v[122:123], v[128:129] op_sel_hi:[0,1,1] neg_lo:[0,0,1] neg_hi:[0,0,1]
	v_pk_fma_f32 v[110:111], v[110:111], v[122:123], v[128:129] op_sel_hi:[0,1,1]
	v_pk_mul_f32 v[122:123], v[80:81], v[124:125] op_sel:[0,1] op_sel_hi:[0,0]
	v_pk_fma_f32 v[128:129], v[112:113], v[124:125], v[122:123] op_sel_hi:[0,1,1] neg_lo:[0,0,1] neg_hi:[0,0,1]
	v_pk_fma_f32 v[122:123], v[112:113], v[124:125], v[122:123] op_sel_hi:[0,1,1]
	v_mov_b32_e32 v129, v123
	v_mov_b32_e32 v153, v111
	v_pk_mul_f32 v[124:125], v[128:129], s[6:7] op_sel_hi:[1,0]
	v_pk_mul_f32 v[154:155], v[152:153], s[6:7] op_sel_hi:[1,0]
	s_and_b64 s[6:7], s[44:45], exec
	v_readlane_b32 s6, v252, 32
	v_readlane_b32 s7, v252, 33
	s_cselect_b32 s7, s7, s29
	s_cselect_b32 s6, s6, s28
	v_cndmask_b32_e64 v117, v111, v155, s[44:45]
	v_lshl_add_u64 v[110:111], s[6:7], 0, v[126:127]
	s_lshl_b32 s6, s59, 1
	s_mov_b32 s7, s93
	v_lshl_add_u64 v[110:111], v[110:111], 0, s[6:7]
	v_lshlrev_b32_e32 v80, 1, v134
	v_cndmask_b32_e64 v113, v128, v124, s[44:45]
	v_cndmask_b32_e64 v112, v123, v125, s[44:45]
	v_cndmask_b32_e64 v121, v152, v154, s[44:45]
	v_lshl_add_u64 v[110:111], v[110:111], 0, v[80:81]
	v_cvt_pk_bf16_f32 v122, v121, v117
	v_cvt_pk_bf16_f32 v123, v113, v112
	global_store_dwordx2 v[110:111], v[122:123], off
	s_and_saveexec_b64 s[12:13], s[4:5]
	s_cbranch_execz .LBB0_1969
	v_readlane_b32 s6, v250, 37
	v_readlane_b32 s7, v250, 38
	v_or_b32_e32 v80, v116, v134
	s_nop 0
	v_mov_b64_e32 v[122:123], s[6:7]
	v_mad_i64_i32 v[122:123], s[6:7], v80, s9, v[122:123]
	v_mul_f32_e32 v80, v120, v121
	v_bfe_u32 v121, v80, 16, 1
	v_lshl_add_u64 v[122:123], v[114:115], 1, v[122:123]
	v_add3_u32 v80, v80, v121, s89
	global_store_short_d16_hi v[122:123], v80, off
	v_mul_f32_e32 v80, v120, v117
	v_bfe_u32 v117, v80, 16, 1
	v_add_co_u32_e32 v124, vcc, 0x1000, v122
	v_add3_u32 v80, v80, v117, s89
	s_nop 0
	v_addc_co_u32_e32 v125, vcc, 0, v123, vcc
	global_store_short_d16_hi v[124:125], v80, off offset:32
	v_mul_f32_e32 v80, v120, v113
	v_bfe_u32 v113, v80, 16, 1
	v_add_co_u32_e32 v124, vcc, 0x2000, v122
	v_add3_u32 v80, v80, v113, s89
	s_nop 0
	v_addc_co_u32_e32 v125, vcc, 0, v123, vcc
	global_store_short_d16_hi v[124:125], v80, off offset:64
	v_mul_f32_e32 v80, v120, v112
	v_bfe_u32 v112, v80, 16, 1
	v_add3_u32 v80, v80, v112, s89
	v_add_co_u32_e32 v112, vcc, 0x3000, v122
	s_nop 1
	v_addc_co_u32_e32 v113, vcc, 0, v123, vcc
	global_store_short_d16_hi v[112:113], v80, off offset:96
.LBB0_1969:
	s_or_b64 exec, exec, s[12:13]
	v_or_b32_e32 v112, v118, v138
	v_mov_b32_e32 v113, v119
	v_lshl_add_u64 v[112:113], v[112:113], 3, s[78:79]
	s_and_b64 s[38:39], exec, s[4:5]
	s_cbranch_scc0 .Lrope_q_1_1
	s_waitcnt vmcnt(7)
	s_branch .Lrope_w_1_1

.Lrope_w_1_1:
	v_mov_b64_e32 v[122:123], v[176:177]
	v_mov_b64_e32 v[124:125], v[178:179]
	v_mov_b32_e32 v80, v109
	s_mov_b32 s6, 0x3d800000
	s_nop 0
	v_pk_mul_f32 v[112:113], v[106:107], v[122:123] op_sel:[1,1] op_sel_hi:[1,0]
	s_nop 0
	v_pk_fma_f32 v[126:127], v[106:107], v[122:123], v[112:113] op_sel_hi:[0,1,1] neg_lo:[0,0,1] neg_hi:[0,0,1]
	v_pk_fma_f32 v[106:107], v[106:107], v[122:123], v[112:113] op_sel_hi:[0,1,1]
	v_pk_mul_f32 v[112:113], v[80:81], v[124:125] op_sel:[0,1] op_sel_hi:[0,0]
	v_pk_fma_f32 v[122:123], v[108:109], v[124:125], v[112:113] op_sel_hi:[0,1,1] neg_lo:[0,0,1] neg_hi:[0,0,1]
	v_pk_fma_f32 v[108:109], v[108:109], v[124:125], v[112:113] op_sel_hi:[0,1,1]
	v_mov_b32_e32 v123, v109
	v_mov_b32_e32 v127, v107
	v_pk_mul_f32 v[112:113], v[122:123], s[6:7] op_sel_hi:[1,0]
	v_pk_mul_f32 v[124:125], v[126:127], s[6:7] op_sel_hi:[1,0]
	v_cndmask_b32_e64 v106, v122, v112, s[44:45]
	v_cndmask_b32_e64 v80, v109, v113, s[44:45]
	v_cndmask_b32_e64 v108, v126, v124, s[44:45]
	v_cndmask_b32_e64 v107, v107, v125, s[44:45]
	v_cvt_pk_bf16_f32 v112, v108, v107
	v_cvt_pk_bf16_f32 v113, v106, v80
	global_store_dwordx2 v[110:111], v[112:113], off offset:32
	s_and_saveexec_b64 s[12:13], s[4:5]
	s_cbranch_execz .LBB0_1971
	v_readlane_b32 s6, v250, 37
	v_readlane_b32 s7, v250, 38
	v_or_b32_e32 v109, v116, v141
	v_mul_f32_e32 v108, v120, v108
	v_mov_b64_e32 v[112:113], s[6:7]
	v_mad_i64_i32 v[112:113], s[6:7], v109, s9, v[112:113]
	v_bfe_u32 v109, v108, 16, 1
	v_lshl_add_u64 v[112:113], v[114:115], 1, v[112:113]
	v_add3_u32 v108, v108, v109, s89
	v_mul_f32_e32 v107, v120, v107
	global_store_short_d16_hi v[112:113], v108, off
	v_bfe_u32 v108, v107, 16, 1
	v_add3_u32 v107, v107, v108, s89
	v_add_co_u32_e32 v108, vcc, 0x1000, v112
	v_mul_f32_e32 v106, v120, v106
	s_nop 0
	v_addc_co_u32_e32 v109, vcc, 0, v113, vcc
	global_store_short_d16_hi v[108:109], v107, off offset:32
	v_bfe_u32 v107, v106, 16, 1
	v_add3_u32 v108, v106, v107, s89
	v_add_co_u32_e32 v106, vcc, 0x2000, v112
	v_mul_f32_e32 v80, v120, v80
	s_nop 0
	v_addc_co_u32_e32 v107, vcc, 0, v113, vcc
	global_store_short_d16_hi v[106:107], v108, off offset:64
	v_bfe_u32 v106, v80, 16, 1
	v_add3_u32 v80, v80, v106, s89
	v_add_co_u32_e32 v106, vcc, 0x3000, v112
	s_nop 1
	v_addc_co_u32_e32 v107, vcc, 0, v113, vcc
	global_store_short_d16_hi v[106:107], v80, off offset:96
.LBB0_1971:
	s_or_b64 exec, exec, s[12:13]
	v_or_b32_e32 v106, v118, v140
	v_mov_b32_e32 v107, v119
	v_lshl_add_u64 v[106:107], v[106:107], 3, s[78:79]
	s_and_b64 s[38:39], exec, s[4:5]
	s_cbranch_scc0 .Lrope_q_1_2
	s_waitcnt vmcnt(11)
	s_branch .Lrope_w_1_2

.Lrope_w_1_2:
	v_mov_b64_e32 v[106:107], v[180:181]
	v_mov_b64_e32 v[108:109], v[182:183]
	v_mov_b32_e32 v80, v105
	s_mov_b32 s6, 0x3d800000
	s_nop 0
	v_pk_mul_f32 v[112:113], v[102:103], v[106:107] op_sel:[1,1] op_sel_hi:[1,0]
	s_nop 0
	v_pk_fma_f32 v[122:123], v[102:103], v[106:107], v[112:113] op_sel_hi:[0,1,1] neg_lo:[0,0,1] neg_hi:[0,0,1]
	v_pk_fma_f32 v[102:103], v[102:103], v[106:107], v[112:113] op_sel_hi:[0,1,1]
	v_pk_mul_f32 v[106:107], v[80:81], v[108:109] op_sel:[0,1] op_sel_hi:[0,0]
	v_pk_fma_f32 v[112:113], v[104:105], v[108:109], v[106:107] op_sel_hi:[0,1,1] neg_lo:[0,0,1] neg_hi:[0,0,1]
	v_pk_fma_f32 v[104:105], v[104:105], v[108:109], v[106:107] op_sel_hi:[0,1,1]
	v_mov_b32_e32 v113, v105
	v_mov_b32_e32 v123, v103
	v_pk_mul_f32 v[106:107], v[112:113], s[6:7] op_sel_hi:[1,0]
	v_pk_mul_f32 v[108:109], v[122:123], s[6:7] op_sel_hi:[1,0]
	v_cndmask_b32_e64 v102, v112, v106, s[44:45]
	v_cndmask_b32_e64 v80, v105, v107, s[44:45]
	v_cndmask_b32_e64 v104, v122, v108, s[44:45]
	v_cndmask_b32_e64 v103, v103, v109, s[44:45]
	v_cvt_pk_bf16_f32 v106, v104, v103
	v_cvt_pk_bf16_f32 v107, v102, v80
	global_store_dwordx2 v[110:111], v[106:107], off offset:256
	s_and_saveexec_b64 s[12:13], s[4:5]
	s_cbranch_execz .LBB0_1973
	v_readlane_b32 s6, v250, 37
	v_readlane_b32 s7, v250, 38
	v_or_b32_e32 v105, v116, v143
	v_mul_f32_e32 v104, v120, v104
	v_mov_b64_e32 v[106:107], s[6:7]
	v_mad_i64_i32 v[106:107], s[6:7], v105, s9, v[106:107]
	v_bfe_u32 v105, v104, 16, 1
	v_lshl_add_u64 v[106:107], v[114:115], 1, v[106:107]
	v_add3_u32 v104, v104, v105, s89
	v_mul_f32_e32 v103, v120, v103
	global_store_short_d16_hi v[106:107], v104, off
	v_bfe_u32 v104, v103, 16, 1
	v_add3_u32 v103, v103, v104, s89
	v_add_co_u32_e32 v104, vcc, 0x1000, v106
	v_mul_f32_e32 v102, v120, v102
	s_nop 0
	v_addc_co_u32_e32 v105, vcc, 0, v107, vcc
	global_store_short_d16_hi v[104:105], v103, off offset:32
	v_bfe_u32 v103, v102, 16, 1
	v_add3_u32 v104, v102, v103, s89
	v_add_co_u32_e32 v102, vcc, 0x2000, v106
	v_mul_f32_e32 v80, v120, v80
	s_nop 0
	v_addc_co_u32_e32 v103, vcc, 0, v107, vcc
	global_store_short_d16_hi v[102:103], v104, off offset:64
	v_bfe_u32 v102, v80, 16, 1
	v_add3_u32 v80, v80, v102, s89
	v_add_co_u32_e32 v102, vcc, 0x3000, v106
	s_nop 1
	v_addc_co_u32_e32 v103, vcc, 0, v107, vcc
	global_store_short_d16_hi v[102:103], v80, off offset:96
.LBB0_1973:
	s_or_b64 exec, exec, s[12:13]
	v_or_b32_e32 v118, v118, v142
	v_lshl_add_u64 v[102:103], v[118:119], 3, s[78:79]
	s_and_b64 s[38:39], exec, s[4:5]
	s_cbranch_scc0 .Lrope_q_1_3
	s_waitcnt vmcnt(15)
	s_branch .Lrope_w_1_3

.Lrope_w_1_3:
	v_mov_b64_e32 v[102:103], v[184:185]
	v_mov_b64_e32 v[104:105], v[186:187]
	v_mov_b32_e32 v80, v101
	s_mov_b32 s6, 0x3d800000
	s_nop 0
	v_pk_mul_f32 v[106:107], v[98:99], v[102:103] op_sel:[1,1] op_sel_hi:[1,0]
	s_nop 0
	v_pk_fma_f32 v[108:109], v[98:99], v[102:103], v[106:107] op_sel_hi:[0,1,1] neg_lo:[0,0,1] neg_hi:[0,0,1]
	v_pk_fma_f32 v[98:99], v[98:99], v[102:103], v[106:107] op_sel_hi:[0,1,1]
	v_pk_mul_f32 v[102:103], v[80:81], v[104:105] op_sel:[0,1] op_sel_hi:[0,0]
	v_pk_fma_f32 v[106:107], v[100:101], v[104:105], v[102:103] op_sel_hi:[0,1,1] neg_lo:[0,0,1] neg_hi:[0,0,1]
	v_pk_fma_f32 v[100:101], v[100:101], v[104:105], v[102:103] op_sel_hi:[0,1,1]
	v_mov_b32_e32 v107, v101
	v_mov_b32_e32 v109, v99
	v_pk_mul_f32 v[102:103], v[106:107], s[6:7] op_sel_hi:[1,0]
	v_pk_mul_f32 v[104:105], v[108:109], s[6:7] op_sel_hi:[1,0]
	v_cndmask_b32_e64 v98, v106, v102, s[44:45]
	v_cndmask_b32_e64 v80, v101, v103, s[44:45]
	v_cndmask_b32_e64 v100, v108, v104, s[44:45]
	v_cndmask_b32_e64 v99, v99, v105, s[44:45]
	v_cvt_pk_bf16_f32 v102, v100, v99
	v_cvt_pk_bf16_f32 v103, v98, v80
	global_store_dwordx2 v[110:111], v[102:103], off offset:288
	s_and_saveexec_b64 s[12:13], s[4:5]
	s_cbranch_execz .LBB0_1975
	v_readlane_b32 s4, v250, 37
	v_readlane_b32 s5, v250, 38
	v_or_b32_e32 v101, v116, v164
	v_mul_f32_e32 v100, v120, v100
	v_mov_b64_e32 v[102:103], s[4:5]
	v_mad_i64_i32 v[102:103], s[4:5], v101, s9, v[102:103]
	v_bfe_u32 v101, v100, 16, 1
	v_lshl_add_u64 v[102:103], v[114:115], 1, v[102:103]
	v_add3_u32 v100, v100, v101, s89
	v_mul_f32_e32 v99, v120, v99
	global_store_short_d16_hi v[102:103], v100, off
	v_bfe_u32 v100, v99, 16, 1
	v_add3_u32 v99, v99, v100, s89
	v_add_co_u32_e32 v100, vcc, 0x1000, v102
	v_mul_f32_e32 v98, v120, v98
	s_nop 0
	v_addc_co_u32_e32 v101, vcc, 0, v103, vcc
	global_store_short_d16_hi v[100:101], v99, off offset:32
	v_bfe_u32 v99, v98, 16, 1
	v_add3_u32 v100, v98, v99, s89
	v_add_co_u32_e32 v98, vcc, 0x2000, v102
	v_mul_f32_e32 v80, v120, v80
	s_nop 0
	v_addc_co_u32_e32 v99, vcc, 0, v103, vcc
	global_store_short_d16_hi v[98:99], v100, off offset:64
	v_bfe_u32 v98, v80, 16, 1
	v_add3_u32 v80, v80, v98, s89
	v_add_co_u32_e32 v98, vcc, 0x3000, v102
	s_nop 1
	v_addc_co_u32_e32 v99, vcc, 0, v103, vcc
	global_store_short_d16_hi v[98:99], v80, off offset:96

.LBB0_1995:
	s_or_b64 exec, exec, s[12:13]
	v_ashrrev_i32_e32 v103, 31, v102
	v_lshlrev_b64 v[102:103], 7, v[102:103]
	v_cndmask_b32_e64 v103, 0, v103, s[50:51]
	v_cndmask_b32_e64 v102, v234, v102, s[50:51]
	v_ashrrev_i32_e32 v101, 31, v100
	v_lshlrev_b64 v[110:111], 11, v[100:101]
	v_lshl_or_b32 v100, v106, 10, s59
	v_or_b32_e32 v106, v102, v136
	v_mov_b32_e32 v107, v103
	v_lshl_add_u64 v[106:107], v[106:107], 3, s[78:79]
	global_load_dwordx4 v[106:109], v[106:107], off
	v_or_b32_e32 v188, v102, v138
	v_mov_b32_e32 v189, v103
	v_lshl_add_u64 v[188:189], v[188:189], 3, s[78:79]
	global_load_dwordx4 v[176:179], v[188:189], off
	v_or_b32_e32 v188, v102, v140
	v_mov_b32_e32 v189, v103
	v_lshl_add_u64 v[188:189], v[188:189], 3, s[78:79]
	global_load_dwordx4 v[180:183], v[188:189], off
	v_or_b32_e32 v188, v102, v142
	v_mov_b32_e32 v189, v103
	v_lshl_add_u64 v[188:189], v[188:189], 3, s[78:79]
	global_load_dwordx4 v[184:187], v[188:189], off
	v_mov_b32_e32 v80, v97
	s_mov_b32 s6, 0x3d800000
	v_ashrrev_i32_e32 v99, 31, v98
	s_waitcnt vmcnt(3)
	v_pk_mul_f32 v[112:113], v[94:95], v[106:107] op_sel:[1,1] op_sel_hi:[1,0]
	s_nop 0
	v_pk_fma_f32 v[114:115], v[94:95], v[106:107], v[112:113] op_sel_hi:[0,1,1] neg_lo:[0,0,1] neg_hi:[0,0,1]
	v_pk_fma_f32 v[94:95], v[94:95], v[106:107], v[112:113] op_sel_hi:[0,1,1]
	v_pk_mul_f32 v[106:107], v[80:81], v[108:109] op_sel:[0,1] op_sel_hi:[0,0]
	v_pk_fma_f32 v[112:113], v[96:97], v[108:109], v[106:107] op_sel_hi:[0,1,1] neg_lo:[0,0,1] neg_hi:[0,0,1]
	v_pk_fma_f32 v[106:107], v[96:97], v[108:109], v[106:107] op_sel_hi:[0,1,1]
	v_mov_b32_e32 v113, v107
	v_mov_b32_e32 v115, v95
	v_pk_mul_f32 v[108:109], v[112:113], s[6:7] op_sel_hi:[1,0]
	v_pk_mul_f32 v[116:117], v[114:115], s[6:7] op_sel_hi:[1,0]
	s_and_b64 s[6:7], s[44:45], exec
	v_readlane_b32 s6, v252, 32
	v_readlane_b32 s7, v252, 33
	s_cselect_b32 s7, s7, s29
	s_cselect_b32 s6, s6, s28
	v_cndmask_b32_e64 v101, v95, v117, s[44:45]
	v_lshl_add_u64 v[94:95], s[6:7], 0, v[110:111]
	s_lshl_b32 s6, s59, 1
	s_mov_b32 s7, s93
	v_lshl_add_u64 v[94:95], v[94:95], 0, s[6:7]
	v_lshlrev_b32_e32 v80, 1, v134
	v_cndmask_b32_e64 v97, v112, v108, s[44:45]
	v_cndmask_b32_e64 v96, v107, v109, s[44:45]
	v_cndmask_b32_e64 v105, v114, v116, s[44:45]
	v_lshl_add_u64 v[94:95], v[94:95], 0, v[80:81]
	v_cvt_pk_bf16_f32 v106, v105, v101
	v_cvt_pk_bf16_f32 v107, v97, v96
	global_store_dwordx2 v[94:95], v[106:107], off
	s_and_saveexec_b64 s[12:13], s[4:5]
	s_cbranch_execz .LBB0_1997
	v_readlane_b32 s6, v250, 37
	v_readlane_b32 s7, v250, 38
	v_or_b32_e32 v80, v100, v134
	s_nop 0
	v_mov_b64_e32 v[106:107], s[6:7]
	v_mad_i64_i32 v[106:107], s[6:7], v80, s9, v[106:107]
	v_mul_f32_e32 v80, v104, v105
	v_bfe_u32 v105, v80, 16, 1
	v_lshl_add_u64 v[106:107], v[98:99], 1, v[106:107]
	v_add3_u32 v80, v80, v105, s89
	global_store_short_d16_hi v[106:107], v80, off
	v_mul_f32_e32 v80, v104, v101
	v_bfe_u32 v101, v80, 16, 1
	v_add_co_u32_e32 v108, vcc, 0x1000, v106
	v_add3_u32 v80, v80, v101, s89
	s_nop 0
	v_addc_co_u32_e32 v109, vcc, 0, v107, vcc
	global_store_short_d16_hi v[108:109], v80, off offset:32
	v_mul_f32_e32 v80, v104, v97
	v_bfe_u32 v97, v80, 16, 1
	v_add_co_u32_e32 v108, vcc, 0x2000, v106
	v_add3_u32 v80, v80, v97, s89
	s_nop 0
	v_addc_co_u32_e32 v109, vcc, 0, v107, vcc
	global_store_short_d16_hi v[108:109], v80, off offset:64
	v_mul_f32_e32 v80, v104, v96
	v_bfe_u32 v96, v80, 16, 1
	v_add3_u32 v80, v80, v96, s89
	v_add_co_u32_e32 v96, vcc, 0x3000, v106
	s_nop 1
	v_addc_co_u32_e32 v97, vcc, 0, v107, vcc
	global_store_short_d16_hi v[96:97], v80, off offset:96
.LBB0_1997:
	s_or_b64 exec, exec, s[12:13]
	v_or_b32_e32 v96, v102, v138
	v_mov_b32_e32 v97, v103
	v_lshl_add_u64 v[96:97], v[96:97], 3, s[78:79]
	s_and_b64 s[38:39], exec, s[4:5]
	s_cbranch_scc0 .Lrope_q_2_1
	s_waitcnt vmcnt(7)
	s_branch .Lrope_w_2_1

.Lrope_w_2_1:
	v_mov_b64_e32 v[106:107], v[176:177]
	v_mov_b64_e32 v[108:109], v[178:179]
	v_mov_b32_e32 v80, v93
	s_mov_b32 s6, 0x3d800000
	s_nop 0
	v_pk_mul_f32 v[96:97], v[90:91], v[106:107] op_sel:[1,1] op_sel_hi:[1,0]
	s_nop 0
	v_pk_fma_f32 v[110:111], v[90:91], v[106:107], v[96:97] op_sel_hi:[0,1,1] neg_lo:[0,0,1] neg_hi:[0,0,1]
	v_pk_fma_f32 v[90:91], v[90:91], v[106:107], v[96:97] op_sel_hi:[0,1,1]
	v_pk_mul_f32 v[96:97], v[80:81], v[108:109] op_sel:[0,1] op_sel_hi:[0,0]
	v_pk_fma_f32 v[106:107], v[92:93], v[108:109], v[96:97] op_sel_hi:[0,1,1] neg_lo:[0,0,1] neg_hi:[0,0,1]
	v_pk_fma_f32 v[92:93], v[92:93], v[108:109], v[96:97] op_sel_hi:[0,1,1]
	v_mov_b32_e32 v107, v93
	v_mov_b32_e32 v111, v91
	v_pk_mul_f32 v[96:97], v[106:107], s[6:7] op_sel_hi:[1,0]
	v_pk_mul_f32 v[108:109], v[110:111], s[6:7] op_sel_hi:[1,0]
	v_cndmask_b32_e64 v90, v106, v96, s[44:45]
	v_cndmask_b32_e64 v80, v93, v97, s[44:45]
	v_cndmask_b32_e64 v92, v110, v108, s[44:45]
	v_cndmask_b32_e64 v91, v91, v109, s[44:45]
	v_cvt_pk_bf16_f32 v96, v92, v91
	v_cvt_pk_bf16_f32 v97, v90, v80
	global_store_dwordx2 v[94:95], v[96:97], off offset:32
	s_and_saveexec_b64 s[12:13], s[4:5]
	s_cbranch_execz .LBB0_1999
	v_readlane_b32 s6, v250, 37
	v_readlane_b32 s7, v250, 38
	v_or_b32_e32 v93, v100, v141
	v_mul_f32_e32 v92, v104, v92
	v_mov_b64_e32 v[96:97], s[6:7]
	v_mad_i64_i32 v[96:97], s[6:7], v93, s9, v[96:97]
	v_bfe_u32 v93, v92, 16, 1
	v_lshl_add_u64 v[96:97], v[98:99], 1, v[96:97]
	v_add3_u32 v92, v92, v93, s89
	v_mul_f32_e32 v91, v104, v91
	global_store_short_d16_hi v[96:97], v92, off
	v_bfe_u32 v92, v91, 16, 1
	v_add3_u32 v91, v91, v92, s89
	v_add_co_u32_e32 v92, vcc, 0x1000, v96
	v_mul_f32_e32 v90, v104, v90
	s_nop 0
	v_addc_co_u32_e32 v93, vcc, 0, v97, vcc
	global_store_short_d16_hi v[92:93], v91, off offset:32
	v_bfe_u32 v91, v90, 16, 1
	v_add3_u32 v92, v90, v91, s89
	v_add_co_u32_e32 v90, vcc, 0x2000, v96
	v_mul_f32_e32 v80, v104, v80
	s_nop 0
	v_addc_co_u32_e32 v91, vcc, 0, v97, vcc
	global_store_short_d16_hi v[90:91], v92, off offset:64
	v_bfe_u32 v90, v80, 16, 1
	v_add3_u32 v80, v80, v90, s89
	v_add_co_u32_e32 v90, vcc, 0x3000, v96
	s_nop 1
	v_addc_co_u32_e32 v91, vcc, 0, v97, vcc
	global_store_short_d16_hi v[90:91], v80, off offset:96
.LBB0_1999:
	s_or_b64 exec, exec, s[12:13]
	v_or_b32_e32 v90, v102, v140
	v_mov_b32_e32 v91, v103
	v_lshl_add_u64 v[90:91], v[90:91], 3, s[78:79]
	s_and_b64 s[38:39], exec, s[4:5]
	s_cbranch_scc0 .Lrope_q_2_2
	s_waitcnt vmcnt(11)
	s_branch .Lrope_w_2_2

.Lrope_w_2_2:
	v_mov_b64_e32 v[90:91], v[180:181]
	v_mov_b64_e32 v[92:93], v[182:183]
	v_mov_b32_e32 v80, v89
	s_mov_b32 s6, 0x3d800000
	s_nop 0
	v_pk_mul_f32 v[96:97], v[86:87], v[90:91] op_sel:[1,1] op_sel_hi:[1,0]
	s_nop 0
	v_pk_fma_f32 v[106:107], v[86:87], v[90:91], v[96:97] op_sel_hi:[0,1,1] neg_lo:[0,0,1] neg_hi:[0,0,1]
	v_pk_fma_f32 v[86:87], v[86:87], v[90:91], v[96:97] op_sel_hi:[0,1,1]
	v_pk_mul_f32 v[90:91], v[80:81], v[92:93] op_sel:[0,1] op_sel_hi:[0,0]
	v_pk_fma_f32 v[96:97], v[88:89], v[92:93], v[90:91] op_sel_hi:[0,1,1] neg_lo:[0,0,1] neg_hi:[0,0,1]
	v_pk_fma_f32 v[88:89], v[88:89], v[92:93], v[90:91] op_sel_hi:[0,1,1]
	v_mov_b32_e32 v97, v89
	v_mov_b32_e32 v107, v87
	v_pk_mul_f32 v[90:91], v[96:97], s[6:7] op_sel_hi:[1,0]
	v_pk_mul_f32 v[92:93], v[106:107], s[6:7] op_sel_hi:[1,0]
	v_cndmask_b32_e64 v86, v96, v90, s[44:45]
	v_cndmask_b32_e64 v80, v89, v91, s[44:45]
	v_cndmask_b32_e64 v88, v106, v92, s[44:45]
	v_cndmask_b32_e64 v87, v87, v93, s[44:45]
	v_cvt_pk_bf16_f32 v90, v88, v87
	v_cvt_pk_bf16_f32 v91, v86, v80
	global_store_dwordx2 v[94:95], v[90:91], off offset:256
	s_and_saveexec_b64 s[12:13], s[4:5]
	s_cbranch_execz .LBB0_2001
	v_readlane_b32 s6, v250, 37
	v_readlane_b32 s7, v250, 38
	v_or_b32_e32 v89, v100, v143
	v_mul_f32_e32 v88, v104, v88
	v_mov_b64_e32 v[90:91], s[6:7]
	v_mad_i64_i32 v[90:91], s[6:7], v89, s9, v[90:91]
	v_bfe_u32 v89, v88, 16, 1
	v_lshl_add_u64 v[90:91], v[98:99], 1, v[90:91]
	v_add3_u32 v88, v88, v89, s89
	v_mul_f32_e32 v87, v104, v87
	global_store_short_d16_hi v[90:91], v88, off
	v_bfe_u32 v88, v87, 16, 1
	v_add3_u32 v87, v87, v88, s89
	v_add_co_u32_e32 v88, vcc, 0x1000, v90
	v_mul_f32_e32 v86, v104, v86
	s_nop 0
	v_addc_co_u32_e32 v89, vcc, 0, v91, vcc
	global_store_short_d16_hi v[88:89], v87, off offset:32
	v_bfe_u32 v87, v86, 16, 1
	v_add3_u32 v88, v86, v87, s89
	v_add_co_u32_e32 v86, vcc, 0x2000, v90
	v_mul_f32_e32 v80, v104, v80
	s_nop 0
	v_addc_co_u32_e32 v87, vcc, 0, v91, vcc
	global_store_short_d16_hi v[86:87], v88, off offset:64
	v_bfe_u32 v86, v80, 16, 1
	v_add3_u32 v80, v80, v86, s89
	v_add_co_u32_e32 v86, vcc, 0x3000, v90
	s_nop 1
	v_addc_co_u32_e32 v87, vcc, 0, v91, vcc
	global_store_short_d16_hi v[86:87], v80, off offset:96
.LBB0_2001:
	s_or_b64 exec, exec, s[12:13]
	v_or_b32_e32 v102, v102, v142
	v_lshl_add_u64 v[86:87], v[102:103], 3, s[78:79]
	s_and_b64 s[38:39], exec, s[4:5]
	s_cbranch_scc0 .Lrope_q_2_3
	s_waitcnt vmcnt(15)
	s_branch .Lrope_w_2_3

.Lrope_w_2_3:
	v_mov_b64_e32 v[86:87], v[184:185]
	v_mov_b64_e32 v[88:89], v[186:187]
	v_mov_b32_e32 v80, v85
	s_mov_b32 s6, 0x3d800000
	s_nop 0
	v_pk_mul_f32 v[90:91], v[82:83], v[86:87] op_sel:[1,1] op_sel_hi:[1,0]
	s_nop 0
	v_pk_fma_f32 v[92:93], v[82:83], v[86:87], v[90:91] op_sel_hi:[0,1,1] neg_lo:[0,0,1] neg_hi:[0,0,1]
	v_pk_fma_f32 v[82:83], v[82:83], v[86:87], v[90:91] op_sel_hi:[0,1,1]
	v_pk_mul_f32 v[86:87], v[80:81], v[88:89] op_sel:[0,1] op_sel_hi:[0,0]
	v_pk_fma_f32 v[90:91], v[84:85], v[88:89], v[86:87] op_sel_hi:[0,1,1] neg_lo:[0,0,1] neg_hi:[0,0,1]
	v_pk_fma_f32 v[84:85], v[84:85], v[88:89], v[86:87] op_sel_hi:[0,1,1]
	v_mov_b32_e32 v91, v85
	v_mov_b32_e32 v93, v83
	v_pk_mul_f32 v[86:87], v[90:91], s[6:7] op_sel_hi:[1,0]
	v_pk_mul_f32 v[88:89], v[92:93], s[6:7] op_sel_hi:[1,0]
	v_cndmask_b32_e64 v82, v90, v86, s[44:45]
	v_cndmask_b32_e64 v80, v85, v87, s[44:45]
	v_cndmask_b32_e64 v84, v92, v88, s[44:45]
	v_cndmask_b32_e64 v83, v83, v89, s[44:45]
	v_cvt_pk_bf16_f32 v86, v84, v83
	v_cvt_pk_bf16_f32 v87, v82, v80
	global_store_dwordx2 v[94:95], v[86:87], off offset:288
	s_and_saveexec_b64 s[12:13], s[4:5]
	s_cbranch_execz .LBB0_2003
	v_readlane_b32 s4, v250, 37
	v_readlane_b32 s5, v250, 38
	v_or_b32_e32 v85, v100, v164
	v_mul_f32_e32 v84, v104, v84
	v_mov_b64_e32 v[86:87], s[4:5]
	v_mad_i64_i32 v[86:87], s[4:5], v85, s9, v[86:87]
	v_bfe_u32 v85, v84, 16, 1
	v_lshl_add_u64 v[86:87], v[98:99], 1, v[86:87]
	v_add3_u32 v84, v84, v85, s89
	v_mul_f32_e32 v83, v104, v83
	global_store_short_d16_hi v[86:87], v84, off
	v_bfe_u32 v84, v83, 16, 1
	v_add3_u32 v83, v83, v84, s89
	v_add_co_u32_e32 v84, vcc, 0x1000, v86
	v_mul_f32_e32 v82, v104, v82
	s_nop 0
	v_addc_co_u32_e32 v85, vcc, 0, v87, vcc
	global_store_short_d16_hi v[84:85], v83, off offset:32
	v_bfe_u32 v83, v82, 16, 1
	v_add3_u32 v84, v82, v83, s89
	v_add_co_u32_e32 v82, vcc, 0x2000, v86
	v_mul_f32_e32 v80, v104, v80
	s_nop 0
	v_addc_co_u32_e32 v83, vcc, 0, v87, vcc
	global_store_short_d16_hi v[82:83], v84, off offset:64
	v_bfe_u32 v82, v80, 16, 1
	v_add3_u32 v80, v80, v82, s89
	v_add_co_u32_e32 v82, vcc, 0x3000, v86
	s_nop 1
	v_addc_co_u32_e32 v83, vcc, 0, v87, vcc
	global_store_short_d16_hi v[82:83], v80, off offset:96

.LBB0_2023:
	s_or_b64 exec, exec, s[12:13]
	v_ashrrev_i32_e32 v87, 31, v86
	v_lshlrev_b64 v[86:87], 7, v[86:87]
	v_cndmask_b32_e64 v87, 0, v87, s[50:51]
	v_cndmask_b32_e64 v86, v234, v86, s[50:51]
	v_ashrrev_i32_e32 v85, 31, v84
	v_lshlrev_b64 v[94:95], 11, v[84:85]
	v_lshl_or_b32 v84, v90, 10, s59
	v_or_b32_e32 v90, v86, v136
	v_mov_b32_e32 v91, v87
	v_lshl_add_u64 v[90:91], v[90:91], 3, s[78:79]
	global_load_dwordx4 v[90:93], v[90:91], off
	v_or_b32_e32 v188, v86, v138
	v_mov_b32_e32 v189, v87
	v_lshl_add_u64 v[188:189], v[188:189], 3, s[78:79]
	global_load_dwordx4 v[176:179], v[188:189], off
	v_or_b32_e32 v188, v86, v140
	v_mov_b32_e32 v189, v87
	v_lshl_add_u64 v[188:189], v[188:189], 3, s[78:79]
	global_load_dwordx4 v[180:183], v[188:189], off
	v_or_b32_e32 v188, v86, v142
	v_mov_b32_e32 v189, v87
	v_lshl_add_u64 v[188:189], v[188:189], 3, s[78:79]
	global_load_dwordx4 v[184:187], v[188:189], off
	s_mov_b32 s6, 0x3d800000
	v_lshlrev_b32_e32 v80, 1, v134
	v_ashrrev_i32_e32 v83, 31, v82
	s_waitcnt vmcnt(3)
	v_pk_mul_f32 v[96:97], v[76:77], v[90:91] op_sel:[1,1] op_sel_hi:[1,0]
	s_nop 0
	v_pk_fma_f32 v[98:99], v[76:77], v[90:91], v[96:97] op_sel_hi:[0,1,1] neg_lo:[0,0,1] neg_hi:[0,0,1]
	v_pk_fma_f32 v[76:77], v[76:77], v[90:91], v[96:97] op_sel_hi:[0,1,1]
	v_mov_b32_e32 v76, v79
	v_pk_mul_f32 v[90:91], v[76:77], v[92:93] op_sel:[0,1] op_sel_hi:[0,0]
	v_pk_fma_f32 v[96:97], v[78:79], v[92:93], v[90:91] op_sel_hi:[0,1,1] neg_lo:[0,0,1] neg_hi:[0,0,1]
	v_pk_fma_f32 v[90:91], v[78:79], v[92:93], v[90:91] op_sel_hi:[0,1,1]
	v_mov_b32_e32 v97, v91
	v_mov_b32_e32 v99, v77
	v_pk_mul_f32 v[92:93], v[96:97], s[6:7] op_sel_hi:[1,0]
	v_pk_mul_f32 v[100:101], v[98:99], s[6:7] op_sel_hi:[1,0]
	s_and_b64 s[6:7], s[44:45], exec
	v_readlane_b32 s6, v252, 32
	v_readlane_b32 s7, v252, 33
	s_cselect_b32 s7, s7, s29
	s_cselect_b32 s6, s6, s28
	v_cndmask_b32_e64 v85, v77, v101, s[44:45]
	v_lshl_add_u64 v[76:77], s[6:7], 0, v[94:95]
	s_lshl_b32 s6, s59, 1
	s_mov_b32 s7, s93
	v_lshl_add_u64 v[76:77], v[76:77], 0, s[6:7]
	v_cndmask_b32_e64 v79, v96, v92, s[44:45]
	v_cndmask_b32_e64 v78, v91, v93, s[44:45]
	v_cndmask_b32_e64 v89, v98, v100, s[44:45]
	v_lshl_add_u64 v[76:77], v[76:77], 0, v[80:81]
	v_cvt_pk_bf16_f32 v90, v89, v85
	v_cvt_pk_bf16_f32 v91, v79, v78
	global_store_dwordx2 v[76:77], v[90:91], off
	s_and_saveexec_b64 s[12:13], s[4:5]
	s_cbranch_execz .LBB0_2025
	v_readlane_b32 s6, v250, 37
	v_readlane_b32 s7, v250, 38
	v_or_b32_e32 v80, v84, v134
	v_mul_f32_e32 v79, v88, v79
	v_mov_b64_e32 v[90:91], s[6:7]
	v_mad_i64_i32 v[90:91], s[6:7], v80, s9, v[90:91]
	v_mul_f32_e32 v80, v88, v89
	v_bfe_u32 v89, v80, 16, 1
	v_lshl_add_u64 v[90:91], v[82:83], 1, v[90:91]
	v_add3_u32 v80, v80, v89, s89
	global_store_short_d16_hi v[90:91], v80, off
	v_mul_f32_e32 v80, v88, v85
	v_bfe_u32 v85, v80, 16, 1
	v_add_co_u32_e32 v92, vcc, 0x1000, v90
	v_add3_u32 v80, v80, v85, s89
	s_nop 0
	v_addc_co_u32_e32 v93, vcc, 0, v91, vcc
	global_store_short_d16_hi v[92:93], v80, off offset:32
	v_bfe_u32 v80, v79, 16, 1
	v_add_co_u32_e32 v92, vcc, 0x2000, v90
	v_add3_u32 v79, v79, v80, s89
	s_nop 0
	v_addc_co_u32_e32 v93, vcc, 0, v91, vcc
	v_mul_f32_e32 v78, v88, v78
	global_store_short_d16_hi v[92:93], v79, off offset:64
	v_bfe_u32 v79, v78, 16, 1
	v_add3_u32 v80, v78, v79, s89
	v_add_co_u32_e32 v78, vcc, 0x3000, v90
	s_nop 1
	v_addc_co_u32_e32 v79, vcc, 0, v91, vcc
	global_store_short_d16_hi v[78:79], v80, off offset:96
.LBB0_2025:
	s_or_b64 exec, exec, s[12:13]
	v_or_b32_e32 v78, v86, v138
	v_mov_b32_e32 v79, v87
	v_lshl_add_u64 v[78:79], v[78:79], 3, s[78:79]
	s_and_b64 s[38:39], exec, s[4:5]
	s_cbranch_scc0 .Lrope_q_3_1
	s_waitcnt vmcnt(7)
	s_branch .Lrope_w_3_1

.Lrope_w_3_1:
	v_mov_b64_e32 v[90:91], v[176:177]
	v_mov_b64_e32 v[92:93], v[178:179]
	s_mov_b32 s6, 0x3d800000
	s_nop 0
	v_pk_mul_f32 v[78:79], v[72:73], v[90:91] op_sel:[1,1] op_sel_hi:[1,0]
	s_nop 0
	v_pk_fma_f32 v[94:95], v[72:73], v[90:91], v[78:79] op_sel_hi:[0,1,1] neg_lo:[0,0,1] neg_hi:[0,0,1]
	v_pk_fma_f32 v[78:79], v[72:73], v[90:91], v[78:79] op_sel_hi:[0,1,1]
	v_mov_b32_e32 v72, v75
	v_pk_mul_f32 v[72:73], v[72:73], v[92:93] op_sel:[0,1] op_sel_hi:[0,0]
	v_pk_fma_f32 v[90:91], v[74:75], v[92:93], v[72:73] op_sel_hi:[0,1,1] neg_lo:[0,0,1] neg_hi:[0,0,1]
	v_pk_fma_f32 v[74:75], v[74:75], v[92:93], v[72:73] op_sel_hi:[0,1,1]
	v_mov_b32_e32 v91, v75
	v_mov_b32_e32 v95, v79
	v_pk_mul_f32 v[92:93], v[90:91], s[6:7] op_sel_hi:[1,0]
	v_pk_mul_f32 v[96:97], v[94:95], s[6:7] op_sel_hi:[1,0]
	v_cndmask_b32_e64 v73, v90, v92, s[44:45]
	v_cndmask_b32_e64 v72, v75, v93, s[44:45]
	v_cndmask_b32_e64 v75, v94, v96, s[44:45]
	v_cndmask_b32_e64 v74, v79, v97, s[44:45]
	v_cvt_pk_bf16_f32 v78, v75, v74
	v_cvt_pk_bf16_f32 v79, v73, v72
	global_store_dwordx2 v[76:77], v[78:79], off offset:32
	s_and_saveexec_b64 s[12:13], s[4:5]
	s_cbranch_execz .LBB0_2027
	v_readlane_b32 s6, v250, 37
	v_readlane_b32 s7, v250, 38
	v_or_b32_e32 v80, v84, v141
	v_mul_f32_e32 v75, v88, v75
	v_mov_b64_e32 v[78:79], s[6:7]
	v_mad_i64_i32 v[78:79], s[6:7], v80, s9, v[78:79]
	v_bfe_u32 v80, v75, 16, 1
	v_lshl_add_u64 v[78:79], v[82:83], 1, v[78:79]
	v_add3_u32 v75, v75, v80, s89
	v_mul_f32_e32 v74, v88, v74
	global_store_short_d16_hi v[78:79], v75, off
	v_bfe_u32 v75, v74, 16, 1
	v_add3_u32 v80, v74, v75, s89
	v_add_co_u32_e32 v74, vcc, 0x1000, v78
	v_mul_f32_e32 v73, v88, v73
	s_nop 0
	v_addc_co_u32_e32 v75, vcc, 0, v79, vcc
	global_store_short_d16_hi v[74:75], v80, off offset:32
	v_bfe_u32 v74, v73, 16, 1
	v_add3_u32 v73, v73, v74, s89
	v_add_co_u32_e32 v74, vcc, 0x2000, v78
	v_mul_f32_e32 v72, v88, v72
	s_nop 0
	v_addc_co_u32_e32 v75, vcc, 0, v79, vcc
	global_store_short_d16_hi v[74:75], v73, off offset:64
	v_bfe_u32 v73, v72, 16, 1
	v_add3_u32 v74, v72, v73, s89
	v_add_co_u32_e32 v72, vcc, 0x3000, v78
	s_nop 1
	v_addc_co_u32_e32 v73, vcc, 0, v79, vcc
	global_store_short_d16_hi v[72:73], v74, off offset:96
.LBB0_2027:
	s_or_b64 exec, exec, s[12:13]
	v_or_b32_e32 v72, v86, v140
	v_mov_b32_e32 v73, v87
	v_lshl_add_u64 v[72:73], v[72:73], 3, s[78:79]
	s_and_b64 s[38:39], exec, s[4:5]
	s_cbranch_scc0 .Lrope_q_3_2
	s_waitcnt vmcnt(11)
	s_branch .Lrope_w_3_2

.Lrope_w_3_2:
	v_mov_b64_e32 v[72:73], v[180:181]
	v_mov_b64_e32 v[74:75], v[182:183]
	s_mov_b32 s6, 0x3d800000
	s_nop 0
	v_pk_mul_f32 v[78:79], v[68:69], v[72:73] op_sel:[1,1] op_sel_hi:[1,0]
	s_nop 0
	v_pk_fma_f32 v[90:91], v[68:69], v[72:73], v[78:79] op_sel_hi:[0,1,1] neg_lo:[0,0,1] neg_hi:[0,0,1]
	v_pk_fma_f32 v[72:73], v[68:69], v[72:73], v[78:79] op_sel_hi:[0,1,1]
	v_mov_b32_e32 v68, v71
	v_pk_mul_f32 v[68:69], v[68:69], v[74:75] op_sel:[0,1] op_sel_hi:[0,0]
	v_pk_fma_f32 v[78:79], v[70:71], v[74:75], v[68:69] op_sel_hi:[0,1,1] neg_lo:[0,0,1] neg_hi:[0,0,1]
	v_pk_fma_f32 v[70:71], v[70:71], v[74:75], v[68:69] op_sel_hi:[0,1,1]
	v_mov_b32_e32 v79, v71
	v_mov_b32_e32 v91, v73
	v_pk_mul_f32 v[74:75], v[78:79], s[6:7] op_sel_hi:[1,0]
	v_pk_mul_f32 v[92:93], v[90:91], s[6:7] op_sel_hi:[1,0]
	v_cndmask_b32_e64 v69, v78, v74, s[44:45]
	v_cndmask_b32_e64 v68, v71, v75, s[44:45]
	v_cndmask_b32_e64 v71, v90, v92, s[44:45]
	v_cndmask_b32_e64 v70, v73, v93, s[44:45]
	v_cvt_pk_bf16_f32 v72, v71, v70
	v_cvt_pk_bf16_f32 v73, v69, v68
	global_store_dwordx2 v[76:77], v[72:73], off offset:256
	s_and_saveexec_b64 s[12:13], s[4:5]
	s_cbranch_execz .LBB0_2029
	v_readlane_b32 s6, v250, 37
	v_readlane_b32 s7, v250, 38
	v_or_b32_e32 v74, v84, v143
	v_mul_f32_e32 v71, v88, v71
	v_mov_b64_e32 v[72:73], s[6:7]
	v_mad_i64_i32 v[72:73], s[6:7], v74, s9, v[72:73]
	v_bfe_u32 v74, v71, 16, 1
	v_lshl_add_u64 v[72:73], v[82:83], 1, v[72:73]
	v_add3_u32 v71, v71, v74, s89
	v_mul_f32_e32 v70, v88, v70
	global_store_short_d16_hi v[72:73], v71, off
	v_bfe_u32 v71, v70, 16, 1
	v_add3_u32 v74, v70, v71, s89
	v_add_co_u32_e32 v70, vcc, 0x1000, v72
	v_mul_f32_e32 v69, v88, v69
	s_nop 0
	v_addc_co_u32_e32 v71, vcc, 0, v73, vcc
	global_store_short_d16_hi v[70:71], v74, off offset:32
	v_bfe_u32 v70, v69, 16, 1
	v_add3_u32 v69, v69, v70, s89
	v_add_co_u32_e32 v70, vcc, 0x2000, v72
	v_mul_f32_e32 v68, v88, v68
	s_nop 0
	v_addc_co_u32_e32 v71, vcc, 0, v73, vcc
	global_store_short_d16_hi v[70:71], v69, off offset:64
	v_bfe_u32 v69, v68, 16, 1
	v_add3_u32 v70, v68, v69, s89
	v_add_co_u32_e32 v68, vcc, 0x3000, v72
	s_nop 1
	v_addc_co_u32_e32 v69, vcc, 0, v73, vcc
	global_store_short_d16_hi v[68:69], v70, off offset:96
.LBB0_2029:
	s_or_b64 exec, exec, s[12:13]
	v_or_b32_e32 v86, v86, v142
	v_lshl_add_u64 v[68:69], v[86:87], 3, s[78:79]
	s_and_b64 s[38:39], exec, s[4:5]
	s_cbranch_scc0 .Lrope_q_3_3
	s_waitcnt vmcnt(15)
	s_branch .Lrope_w_3_3

.Lrope_w_3_3:
	v_mov_b64_e32 v[68:69], v[184:185]
	v_mov_b64_e32 v[70:71], v[186:187]
	s_mov_b32 s6, 0x3d800000
	s_nop 0
	v_pk_mul_f32 v[72:73], v[64:65], v[68:69] op_sel:[1,1] op_sel_hi:[1,0]
	s_nop 0
	v_pk_fma_f32 v[74:75], v[64:65], v[68:69], v[72:73] op_sel_hi:[0,1,1] neg_lo:[0,0,1] neg_hi:[0,0,1]
	v_pk_fma_f32 v[68:69], v[64:65], v[68:69], v[72:73] op_sel_hi:[0,1,1]
	v_mov_b32_e32 v64, v67
	v_pk_mul_f32 v[64:65], v[64:65], v[70:71] op_sel:[0,1] op_sel_hi:[0,0]
	v_pk_fma_f32 v[72:73], v[66:67], v[70:71], v[64:65] op_sel_hi:[0,1,1] neg_lo:[0,0,1] neg_hi:[0,0,1]
	v_pk_fma_f32 v[66:67], v[66:67], v[70:71], v[64:65] op_sel_hi:[0,1,1]
	v_mov_b32_e32 v73, v67
	v_mov_b32_e32 v75, v69
	v_pk_mul_f32 v[70:71], v[72:73], s[6:7] op_sel_hi:[1,0]
	v_pk_mul_f32 v[78:79], v[74:75], s[6:7] op_sel_hi:[1,0]
	v_cndmask_b32_e64 v65, v72, v70, s[44:45]
	v_cndmask_b32_e64 v64, v67, v71, s[44:45]
	v_cndmask_b32_e64 v67, v74, v78, s[44:45]
	v_cndmask_b32_e64 v66, v69, v79, s[44:45]
	v_cvt_pk_bf16_f32 v68, v67, v66
	v_cvt_pk_bf16_f32 v69, v65, v64
	global_store_dwordx2 v[76:77], v[68:69], off offset:288
	s_and_saveexec_b64 s[12:13], s[4:5]
	s_cbranch_execz .LBB0_2031
	v_readlane_b32 s4, v250, 37
	v_readlane_b32 s5, v250, 38
	v_or_b32_e32 v70, v84, v164
	v_mul_f32_e32 v67, v88, v67
	v_mov_b64_e32 v[68:69], s[4:5]
	v_mad_i64_i32 v[68:69], s[4:5], v70, s9, v[68:69]
	v_bfe_u32 v70, v67, 16, 1
	v_lshl_add_u64 v[68:69], v[82:83], 1, v[68:69]
	v_add3_u32 v67, v67, v70, s89
	v_mul_f32_e32 v66, v88, v66
	global_store_short_d16_hi v[68:69], v67, off
	v_bfe_u32 v67, v66, 16, 1
	v_add3_u32 v70, v66, v67, s89
	v_add_co_u32_e32 v66, vcc, 0x1000, v68
	v_mul_f32_e32 v65, v88, v65
	s_nop 0
	v_addc_co_u32_e32 v67, vcc, 0, v69, vcc
	global_store_short_d16_hi v[66:67], v70, off offset:32
	v_bfe_u32 v66, v65, 16, 1
	v_add3_u32 v65, v65, v66, s89
	v_add_co_u32_e32 v66, vcc, 0x2000, v68
	v_mul_f32_e32 v64, v88, v64
	s_nop 0
	v_addc_co_u32_e32 v67, vcc, 0, v69, vcc
	global_store_short_d16_hi v[66:67], v65, off offset:64
	v_bfe_u32 v65, v64, 16, 1
	v_add3_u32 v66, v64, v65, s89
	v_add_co_u32_e32 v64, vcc, 0x3000, v68
	s_nop 1
	v_addc_co_u32_e32 v65, vcc, 0, v69, vcc
	global_store_short_d16_hi v[64:65], v66, off offset:96

.LBB0_2051:
	s_or_b64 exec, exec, s[12:13]
	v_ashrrev_i32_e32 v69, 31, v68
	v_lshlrev_b64 v[68:69], 7, v[68:69]
	v_cndmask_b32_e64 v69, 0, v69, s[50:51]
	v_cndmask_b32_e64 v68, v234, v68, s[50:51]
	v_ashrrev_i32_e32 v67, 31, v66
	v_lshlrev_b64 v[76:77], 11, v[66:67]
	v_lshl_or_b32 v66, v72, 10, s59
	v_or_b32_e32 v72, v68, v136
	v_mov_b32_e32 v73, v69
	v_lshl_add_u64 v[72:73], v[72:73], 3, s[78:79]
	global_load_dwordx4 v[72:75], v[72:73], off
	v_or_b32_e32 v188, v68, v138
	v_mov_b32_e32 v189, v69
	v_lshl_add_u64 v[188:189], v[188:189], 3, s[78:79]
	global_load_dwordx4 v[176:179], v[188:189], off
	v_or_b32_e32 v188, v68, v140
	v_mov_b32_e32 v189, v69
	v_lshl_add_u64 v[188:189], v[188:189], 3, s[78:79]
	global_load_dwordx4 v[180:183], v[188:189], off
	v_or_b32_e32 v188, v68, v142
	v_mov_b32_e32 v189, v69
	v_lshl_add_u64 v[188:189], v[188:189], 3, s[78:79]
	global_load_dwordx4 v[184:187], v[188:189], off
	s_mov_b32 s6, 0x3d800000
	v_lshlrev_b32_e32 v80, 1, v134
	v_ashrrev_i32_e32 v65, 31, v64
	s_waitcnt vmcnt(3)
	v_pk_mul_f32 v[78:79], v[60:61], v[72:73] op_sel:[1,1] op_sel_hi:[1,0]
	s_nop 0
	v_pk_fma_f32 v[82:83], v[60:61], v[72:73], v[78:79] op_sel_hi:[0,1,1] neg_lo:[0,0,1] neg_hi:[0,0,1]
	v_pk_fma_f32 v[60:61], v[60:61], v[72:73], v[78:79] op_sel_hi:[0,1,1]
	v_mov_b32_e32 v60, v63
	v_pk_mul_f32 v[72:73], v[60:61], v[74:75] op_sel:[0,1] op_sel_hi:[0,0]
	v_pk_fma_f32 v[78:79], v[62:63], v[74:75], v[72:73] op_sel_hi:[0,1,1] neg_lo:[0,0,1] neg_hi:[0,0,1]
	v_pk_fma_f32 v[72:73], v[62:63], v[74:75], v[72:73] op_sel_hi:[0,1,1]
	v_mov_b32_e32 v79, v73
	v_mov_b32_e32 v83, v61
	v_pk_mul_f32 v[74:75], v[78:79], s[6:7] op_sel_hi:[1,0]
	v_pk_mul_f32 v[84:85], v[82:83], s[6:7] op_sel_hi:[1,0]
	s_and_b64 s[6:7], s[44:45], exec
	v_readlane_b32 s6, v252, 32
	v_readlane_b32 s7, v252, 33
	s_cselect_b32 s7, s7, s29
	s_cselect_b32 s6, s6, s28
	v_cndmask_b32_e64 v67, v61, v85, s[44:45]
	v_lshl_add_u64 v[60:61], s[6:7], 0, v[76:77]
	s_lshl_b32 s6, s59, 1
	s_mov_b32 s7, s93
	v_lshl_add_u64 v[60:61], v[60:61], 0, s[6:7]
	v_cndmask_b32_e64 v63, v78, v74, s[44:45]
	v_cndmask_b32_e64 v62, v73, v75, s[44:45]
	v_cndmask_b32_e64 v71, v82, v84, s[44:45]
	v_lshl_add_u64 v[60:61], v[60:61], 0, v[80:81]
	v_cvt_pk_bf16_f32 v72, v71, v67
	v_cvt_pk_bf16_f32 v73, v63, v62
	global_store_dwordx2 v[60:61], v[72:73], off
	s_and_saveexec_b64 s[12:13], s[4:5]
	s_cbranch_execz .LBB0_2053
	v_readlane_b32 s6, v250, 37
	v_readlane_b32 s7, v250, 38
	v_or_b32_e32 v74, v66, v134
	v_mul_f32_e32 v71, v70, v71
	v_mov_b64_e32 v[72:73], s[6:7]
	v_mad_i64_i32 v[72:73], s[6:7], v74, s9, v[72:73]
	v_bfe_u32 v74, v71, 16, 1
	v_lshl_add_u64 v[72:73], v[64:65], 1, v[72:73]
	v_add3_u32 v71, v71, v74, s89
	v_mul_f32_e32 v67, v70, v67
	global_store_short_d16_hi v[72:73], v71, off
	v_bfe_u32 v71, v67, 16, 1
	v_add_co_u32_e32 v74, vcc, 0x1000, v72
	v_add3_u32 v67, v67, v71, s89
	s_nop 0
	v_addc_co_u32_e32 v75, vcc, 0, v73, vcc
	v_mul_f32_e32 v63, v70, v63
	global_store_short_d16_hi v[74:75], v67, off offset:32
	v_bfe_u32 v67, v63, 16, 1
	v_add_co_u32_e32 v74, vcc, 0x2000, v72
	v_add3_u32 v63, v63, v67, s89
	s_nop 0
	v_addc_co_u32_e32 v75, vcc, 0, v73, vcc
	v_mul_f32_e32 v62, v70, v62
	global_store_short_d16_hi v[74:75], v63, off offset:64
	v_bfe_u32 v63, v62, 16, 1
	v_add3_u32 v67, v62, v63, s89
	v_add_co_u32_e32 v62, vcc, 0x3000, v72
	s_nop 1
	v_addc_co_u32_e32 v63, vcc, 0, v73, vcc
	global_store_short_d16_hi v[62:63], v67, off offset:96
.LBB0_2053:
	s_or_b64 exec, exec, s[12:13]
	v_or_b32_e32 v62, v68, v138
	v_mov_b32_e32 v63, v69
	v_lshl_add_u64 v[62:63], v[62:63], 3, s[78:79]
	s_and_b64 s[38:39], exec, s[4:5]
	s_cbranch_scc0 .Lrope_q_4_1
	s_waitcnt vmcnt(7)
	s_branch .Lrope_w_4_1

.Lrope_w_4_1:
	v_mov_b64_e32 v[72:73], v[176:177]
	v_mov_b64_e32 v[74:75], v[178:179]
	s_mov_b32 s6, 0x3d800000
	s_nop 0
	v_pk_mul_f32 v[62:63], v[56:57], v[72:73] op_sel:[1,1] op_sel_hi:[1,0]
	s_nop 0
	v_pk_fma_f32 v[76:77], v[56:57], v[72:73], v[62:63] op_sel_hi:[0,1,1] neg_lo:[0,0,1] neg_hi:[0,0,1]
	v_pk_fma_f32 v[62:63], v[56:57], v[72:73], v[62:63] op_sel_hi:[0,1,1]
	v_mov_b32_e32 v56, v59
	v_pk_mul_f32 v[56:57], v[56:57], v[74:75] op_sel:[0,1] op_sel_hi:[0,0]
	v_pk_fma_f32 v[72:73], v[58:59], v[74:75], v[56:57] op_sel_hi:[0,1,1] neg_lo:[0,0,1] neg_hi:[0,0,1]
	v_pk_fma_f32 v[58:59], v[58:59], v[74:75], v[56:57] op_sel_hi:[0,1,1]
	v_mov_b32_e32 v73, v59
	v_mov_b32_e32 v77, v63
	v_pk_mul_f32 v[74:75], v[72:73], s[6:7] op_sel_hi:[1,0]
	v_pk_mul_f32 v[78:79], v[76:77], s[6:7] op_sel_hi:[1,0]
	v_cndmask_b32_e64 v57, v72, v74, s[44:45]
	v_cndmask_b32_e64 v56, v59, v75, s[44:45]
	v_cndmask_b32_e64 v59, v76, v78, s[44:45]
	v_cndmask_b32_e64 v58, v63, v79, s[44:45]
	v_cvt_pk_bf16_f32 v62, v59, v58
	v_cvt_pk_bf16_f32 v63, v57, v56
	global_store_dwordx2 v[60:61], v[62:63], off offset:32
	s_and_saveexec_b64 s[12:13], s[4:5]
	s_cbranch_execz .LBB0_2055
	v_readlane_b32 s6, v250, 37
	v_readlane_b32 s7, v250, 38
	v_or_b32_e32 v67, v66, v141
	v_mul_f32_e32 v59, v70, v59
	v_mov_b64_e32 v[62:63], s[6:7]
	v_mad_i64_i32 v[62:63], s[6:7], v67, s9, v[62:63]
	v_bfe_u32 v67, v59, 16, 1
	v_lshl_add_u64 v[62:63], v[64:65], 1, v[62:63]
	v_add3_u32 v59, v59, v67, s89
	v_mul_f32_e32 v58, v70, v58
	global_store_short_d16_hi v[62:63], v59, off
	v_bfe_u32 v59, v58, 16, 1
	v_add3_u32 v67, v58, v59, s89
	v_add_co_u32_e32 v58, vcc, 0x1000, v62
	v_mul_f32_e32 v57, v70, v57
	s_nop 0
	v_addc_co_u32_e32 v59, vcc, 0, v63, vcc
	global_store_short_d16_hi v[58:59], v67, off offset:32
	v_bfe_u32 v58, v57, 16, 1
	v_add3_u32 v57, v57, v58, s89
	v_add_co_u32_e32 v58, vcc, 0x2000, v62
	v_mul_f32_e32 v56, v70, v56
	s_nop 0
	v_addc_co_u32_e32 v59, vcc, 0, v63, vcc
	global_store_short_d16_hi v[58:59], v57, off offset:64
	v_bfe_u32 v57, v56, 16, 1
	v_add3_u32 v58, v56, v57, s89
	v_add_co_u32_e32 v56, vcc, 0x3000, v62
	s_nop 1
	v_addc_co_u32_e32 v57, vcc, 0, v63, vcc
	global_store_short_d16_hi v[56:57], v58, off offset:96
.LBB0_2055:
	s_or_b64 exec, exec, s[12:13]
	v_or_b32_e32 v56, v68, v140
	v_mov_b32_e32 v57, v69
	v_lshl_add_u64 v[56:57], v[56:57], 3, s[78:79]
	s_and_b64 s[38:39], exec, s[4:5]
	s_cbranch_scc0 .Lrope_q_4_2
	s_waitcnt vmcnt(11)
	s_branch .Lrope_w_4_2

.Lrope_w_4_2:
	v_mov_b64_e32 v[56:57], v[180:181]
	v_mov_b64_e32 v[58:59], v[182:183]
	s_mov_b32 s6, 0x3d800000
	s_nop 0
	v_pk_mul_f32 v[62:63], v[52:53], v[56:57] op_sel:[1,1] op_sel_hi:[1,0]
	s_nop 0
	v_pk_fma_f32 v[72:73], v[52:53], v[56:57], v[62:63] op_sel_hi:[0,1,1] neg_lo:[0,0,1] neg_hi:[0,0,1]
	v_pk_fma_f32 v[56:57], v[52:53], v[56:57], v[62:63] op_sel_hi:[0,1,1]
	v_mov_b32_e32 v52, v55
	v_pk_mul_f32 v[52:53], v[52:53], v[58:59] op_sel:[0,1] op_sel_hi:[0,0]
	v_pk_fma_f32 v[62:63], v[54:55], v[58:59], v[52:53] op_sel_hi:[0,1,1] neg_lo:[0,0,1] neg_hi:[0,0,1]
	v_pk_fma_f32 v[54:55], v[54:55], v[58:59], v[52:53] op_sel_hi:[0,1,1]
	v_mov_b32_e32 v63, v55
	v_mov_b32_e32 v73, v57
	v_pk_mul_f32 v[58:59], v[62:63], s[6:7] op_sel_hi:[1,0]
	v_pk_mul_f32 v[74:75], v[72:73], s[6:7] op_sel_hi:[1,0]
	v_cndmask_b32_e64 v53, v62, v58, s[44:45]
	v_cndmask_b32_e64 v52, v55, v59, s[44:45]
	v_cndmask_b32_e64 v55, v72, v74, s[44:45]
	v_cndmask_b32_e64 v54, v57, v75, s[44:45]
	v_cvt_pk_bf16_f32 v56, v55, v54
	v_cvt_pk_bf16_f32 v57, v53, v52
	global_store_dwordx2 v[60:61], v[56:57], off offset:256
	s_and_saveexec_b64 s[12:13], s[4:5]
	s_cbranch_execz .LBB0_2057
	v_readlane_b32 s6, v250, 37
	v_readlane_b32 s7, v250, 38
	v_or_b32_e32 v58, v66, v143
	v_mul_f32_e32 v55, v70, v55
	v_mov_b64_e32 v[56:57], s[6:7]
	v_mad_i64_i32 v[56:57], s[6:7], v58, s9, v[56:57]
	v_bfe_u32 v58, v55, 16, 1
	v_lshl_add_u64 v[56:57], v[64:65], 1, v[56:57]
	v_add3_u32 v55, v55, v58, s89
	v_mul_f32_e32 v54, v70, v54
	global_store_short_d16_hi v[56:57], v55, off
	v_bfe_u32 v55, v54, 16, 1
	v_add3_u32 v58, v54, v55, s89
	v_add_co_u32_e32 v54, vcc, 0x1000, v56
	v_mul_f32_e32 v53, v70, v53
	s_nop 0
	v_addc_co_u32_e32 v55, vcc, 0, v57, vcc
	global_store_short_d16_hi v[54:55], v58, off offset:32
	v_bfe_u32 v54, v53, 16, 1
	v_add3_u32 v53, v53, v54, s89
	v_add_co_u32_e32 v54, vcc, 0x2000, v56
	v_mul_f32_e32 v52, v70, v52
	s_nop 0
	v_addc_co_u32_e32 v55, vcc, 0, v57, vcc
	global_store_short_d16_hi v[54:55], v53, off offset:64
	v_bfe_u32 v53, v52, 16, 1
	v_add3_u32 v54, v52, v53, s89
	v_add_co_u32_e32 v52, vcc, 0x3000, v56
	s_nop 1
	v_addc_co_u32_e32 v53, vcc, 0, v57, vcc
	global_store_short_d16_hi v[52:53], v54, off offset:96
.LBB0_2057:
	s_or_b64 exec, exec, s[12:13]
	v_or_b32_e32 v68, v68, v142
	v_lshl_add_u64 v[52:53], v[68:69], 3, s[78:79]
	s_and_b64 s[38:39], exec, s[4:5]
	s_cbranch_scc0 .Lrope_q_4_3
	s_waitcnt vmcnt(15)
	s_branch .Lrope_w_4_3

.Lrope_w_4_3:
	v_mov_b64_e32 v[52:53], v[184:185]
	v_mov_b64_e32 v[54:55], v[186:187]
	s_mov_b32 s6, 0x3d800000
	s_nop 0
	v_pk_mul_f32 v[56:57], v[48:49], v[52:53] op_sel:[1,1] op_sel_hi:[1,0]
	s_nop 0
	v_pk_fma_f32 v[58:59], v[48:49], v[52:53], v[56:57] op_sel_hi:[0,1,1] neg_lo:[0,0,1] neg_hi:[0,0,1]
	v_pk_fma_f32 v[52:53], v[48:49], v[52:53], v[56:57] op_sel_hi:[0,1,1]
	v_mov_b32_e32 v48, v51
	v_pk_mul_f32 v[48:49], v[48:49], v[54:55] op_sel:[0,1] op_sel_hi:[0,0]
	v_pk_fma_f32 v[56:57], v[50:51], v[54:55], v[48:49] op_sel_hi:[0,1,1] neg_lo:[0,0,1] neg_hi:[0,0,1]
	v_pk_fma_f32 v[50:51], v[50:51], v[54:55], v[48:49] op_sel_hi:[0,1,1]
	v_mov_b32_e32 v57, v51
	v_mov_b32_e32 v59, v53
	v_pk_mul_f32 v[54:55], v[56:57], s[6:7] op_sel_hi:[1,0]
	v_pk_mul_f32 v[62:63], v[58:59], s[6:7] op_sel_hi:[1,0]
	v_cndmask_b32_e64 v49, v56, v54, s[44:45]
	v_cndmask_b32_e64 v48, v51, v55, s[44:45]
	v_cndmask_b32_e64 v51, v58, v62, s[44:45]
	v_cndmask_b32_e64 v50, v53, v63, s[44:45]
	v_cvt_pk_bf16_f32 v52, v51, v50
	v_cvt_pk_bf16_f32 v53, v49, v48
	global_store_dwordx2 v[60:61], v[52:53], off offset:288
	s_and_saveexec_b64 s[12:13], s[4:5]
	s_cbranch_execz .LBB0_2059
	v_readlane_b32 s4, v250, 37
	v_readlane_b32 s5, v250, 38
	v_or_b32_e32 v54, v66, v164
	v_mul_f32_e32 v51, v70, v51
	v_mov_b64_e32 v[52:53], s[4:5]
	v_mad_i64_i32 v[52:53], s[4:5], v54, s9, v[52:53]
	v_bfe_u32 v54, v51, 16, 1
	v_lshl_add_u64 v[52:53], v[64:65], 1, v[52:53]
	v_add3_u32 v51, v51, v54, s89
	v_mul_f32_e32 v50, v70, v50
	global_store_short_d16_hi v[52:53], v51, off
	v_bfe_u32 v51, v50, 16, 1
	v_add3_u32 v54, v50, v51, s89
	v_add_co_u32_e32 v50, vcc, 0x1000, v52
	v_mul_f32_e32 v49, v70, v49
	s_nop 0
	v_addc_co_u32_e32 v51, vcc, 0, v53, vcc
	global_store_short_d16_hi v[50:51], v54, off offset:32
	v_bfe_u32 v50, v49, 16, 1
	v_add3_u32 v49, v49, v50, s89
	v_add_co_u32_e32 v50, vcc, 0x2000, v52
	v_mul_f32_e32 v48, v70, v48
	s_nop 0
	v_addc_co_u32_e32 v51, vcc, 0, v53, vcc
	global_store_short_d16_hi v[50:51], v49, off offset:64
	v_bfe_u32 v49, v48, 16, 1
	v_add3_u32 v50, v48, v49, s89
	v_add_co_u32_e32 v48, vcc, 0x3000, v52
	s_nop 1
	v_addc_co_u32_e32 v49, vcc, 0, v53, vcc
	global_store_short_d16_hi v[48:49], v50, off offset:96

.LBB0_2079:
	s_or_b64 exec, exec, s[12:13]
	v_ashrrev_i32_e32 v53, 31, v52
	v_lshlrev_b64 v[52:53], 7, v[52:53]
	v_cndmask_b32_e64 v53, 0, v53, s[50:51]
	v_cndmask_b32_e64 v52, v234, v52, s[50:51]
	v_ashrrev_i32_e32 v51, 31, v50
	v_lshlrev_b64 v[60:61], 11, v[50:51]
	v_lshl_or_b32 v50, v56, 10, s59
	v_or_b32_e32 v56, v52, v136
	v_mov_b32_e32 v57, v53
	v_lshl_add_u64 v[56:57], v[56:57], 3, s[78:79]
	global_load_dwordx4 v[56:59], v[56:57], off
	v_or_b32_e32 v188, v52, v138
	v_mov_b32_e32 v189, v53
	v_lshl_add_u64 v[188:189], v[188:189], 3, s[78:79]
	global_load_dwordx4 v[176:179], v[188:189], off
	v_or_b32_e32 v188, v52, v140
	v_mov_b32_e32 v189, v53
	v_lshl_add_u64 v[188:189], v[188:189], 3, s[78:79]
	global_load_dwordx4 v[180:183], v[188:189], off
	v_or_b32_e32 v188, v52, v142
	v_mov_b32_e32 v189, v53
	v_lshl_add_u64 v[188:189], v[188:189], 3, s[78:79]
	global_load_dwordx4 v[184:187], v[188:189], off
	s_mov_b32 s6, 0x3d800000
	v_lshlrev_b32_e32 v80, 1, v134
	v_ashrrev_i32_e32 v49, 31, v48
	s_waitcnt vmcnt(3)
	v_pk_mul_f32 v[62:63], v[44:45], v[56:57] op_sel:[1,1] op_sel_hi:[1,0]
	s_nop 0
	v_pk_fma_f32 v[64:65], v[44:45], v[56:57], v[62:63] op_sel_hi:[0,1,1] neg_lo:[0,0,1] neg_hi:[0,0,1]
	v_pk_fma_f32 v[44:45], v[44:45], v[56:57], v[62:63] op_sel_hi:[0,1,1]
	v_mov_b32_e32 v44, v47
	v_pk_mul_f32 v[56:57], v[44:45], v[58:59] op_sel:[0,1] op_sel_hi:[0,0]
	v_pk_fma_f32 v[62:63], v[46:47], v[58:59], v[56:57] op_sel_hi:[0,1,1] neg_lo:[0,0,1] neg_hi:[0,0,1]
	v_pk_fma_f32 v[56:57], v[46:47], v[58:59], v[56:57] op_sel_hi:[0,1,1]
	v_mov_b32_e32 v63, v57
	v_mov_b32_e32 v65, v45
	v_pk_mul_f32 v[58:59], v[62:63], s[6:7] op_sel_hi:[1,0]
	v_pk_mul_f32 v[66:67], v[64:65], s[6:7] op_sel_hi:[1,0]
	s_and_b64 s[6:7], s[44:45], exec
	v_readlane_b32 s6, v252, 32
	v_readlane_b32 s7, v252, 33
	s_cselect_b32 s7, s7, s29
	s_cselect_b32 s6, s6, s28
	v_cndmask_b32_e64 v51, v45, v67, s[44:45]
	v_lshl_add_u64 v[44:45], s[6:7], 0, v[60:61]
	s_lshl_b32 s6, s59, 1
	s_mov_b32 s7, s93
	v_lshl_add_u64 v[44:45], v[44:45], 0, s[6:7]
	v_cndmask_b32_e64 v47, v62, v58, s[44:45]
	v_cndmask_b32_e64 v46, v57, v59, s[44:45]
	v_cndmask_b32_e64 v55, v64, v66, s[44:45]
	v_lshl_add_u64 v[44:45], v[44:45], 0, v[80:81]
	v_cvt_pk_bf16_f32 v56, v55, v51
	v_cvt_pk_bf16_f32 v57, v47, v46
	global_store_dwordx2 v[44:45], v[56:57], off
	s_and_saveexec_b64 s[12:13], s[4:5]
	s_cbranch_execz .LBB0_2081
	v_readlane_b32 s6, v250, 37
	v_readlane_b32 s7, v250, 38
	v_or_b32_e32 v58, v50, v134
	v_mul_f32_e32 v55, v54, v55
	v_mov_b64_e32 v[56:57], s[6:7]
	v_mad_i64_i32 v[56:57], s[6:7], v58, s9, v[56:57]
	v_bfe_u32 v58, v55, 16, 1
	v_lshl_add_u64 v[56:57], v[48:49], 1, v[56:57]
	v_add3_u32 v55, v55, v58, s89
	v_mul_f32_e32 v51, v54, v51
	global_store_short_d16_hi v[56:57], v55, off
	v_bfe_u32 v55, v51, 16, 1
	v_add_co_u32_e32 v58, vcc, 0x1000, v56
	v_add3_u32 v51, v51, v55, s89
	s_nop 0
	v_addc_co_u32_e32 v59, vcc, 0, v57, vcc
	v_mul_f32_e32 v47, v54, v47
	global_store_short_d16_hi v[58:59], v51, off offset:32
	v_bfe_u32 v51, v47, 16, 1
	v_add_co_u32_e32 v58, vcc, 0x2000, v56
	v_add3_u32 v47, v47, v51, s89
	s_nop 0
	v_addc_co_u32_e32 v59, vcc, 0, v57, vcc
	v_mul_f32_e32 v46, v54, v46
	global_store_short_d16_hi v[58:59], v47, off offset:64
	v_bfe_u32 v47, v46, 16, 1
	v_add3_u32 v51, v46, v47, s89
	v_add_co_u32_e32 v46, vcc, 0x3000, v56
	s_nop 1
	v_addc_co_u32_e32 v47, vcc, 0, v57, vcc
	global_store_short_d16_hi v[46:47], v51, off offset:96
.LBB0_2081:
	s_or_b64 exec, exec, s[12:13]
	v_or_b32_e32 v46, v52, v138
	v_mov_b32_e32 v47, v53
	v_lshl_add_u64 v[46:47], v[46:47], 3, s[78:79]
	s_and_b64 s[38:39], exec, s[4:5]
	s_cbranch_scc0 .Lrope_q_5_1
	s_waitcnt vmcnt(7)
	s_branch .Lrope_w_5_1

.Lrope_w_5_1:
	v_mov_b64_e32 v[56:57], v[176:177]
	v_mov_b64_e32 v[58:59], v[178:179]
	s_mov_b32 s6, 0x3d800000
	s_nop 0
	v_pk_mul_f32 v[46:47], v[40:41], v[56:57] op_sel:[1,1] op_sel_hi:[1,0]
	s_nop 0
	v_pk_fma_f32 v[60:61], v[40:41], v[56:57], v[46:47] op_sel_hi:[0,1,1] neg_lo:[0,0,1] neg_hi:[0,0,1]
	v_pk_fma_f32 v[46:47], v[40:41], v[56:57], v[46:47] op_sel_hi:[0,1,1]
	v_mov_b32_e32 v40, v43
	v_pk_mul_f32 v[40:41], v[40:41], v[58:59] op_sel:[0,1] op_sel_hi:[0,0]
	v_pk_fma_f32 v[56:57], v[42:43], v[58:59], v[40:41] op_sel_hi:[0,1,1] neg_lo:[0,0,1] neg_hi:[0,0,1]
	v_pk_fma_f32 v[42:43], v[42:43], v[58:59], v[40:41] op_sel_hi:[0,1,1]
	v_mov_b32_e32 v57, v43
	v_mov_b32_e32 v61, v47
	v_pk_mul_f32 v[58:59], v[56:57], s[6:7] op_sel_hi:[1,0]
	v_pk_mul_f32 v[62:63], v[60:61], s[6:7] op_sel_hi:[1,0]
	v_cndmask_b32_e64 v41, v56, v58, s[44:45]
	v_cndmask_b32_e64 v40, v43, v59, s[44:45]
	v_cndmask_b32_e64 v43, v60, v62, s[44:45]
	v_cndmask_b32_e64 v42, v47, v63, s[44:45]
	v_cvt_pk_bf16_f32 v46, v43, v42
	v_cvt_pk_bf16_f32 v47, v41, v40
	global_store_dwordx2 v[44:45], v[46:47], off offset:32
	s_and_saveexec_b64 s[12:13], s[4:5]
	s_cbranch_execz .LBB0_2083
	v_readlane_b32 s6, v250, 37
	v_readlane_b32 s7, v250, 38
	v_or_b32_e32 v51, v50, v141
	v_mul_f32_e32 v43, v54, v43
	v_mov_b64_e32 v[46:47], s[6:7]
	v_mad_i64_i32 v[46:47], s[6:7], v51, s9, v[46:47]
	v_bfe_u32 v51, v43, 16, 1
	v_lshl_add_u64 v[46:47], v[48:49], 1, v[46:47]
	v_add3_u32 v43, v43, v51, s89
	v_mul_f32_e32 v42, v54, v42
	global_store_short_d16_hi v[46:47], v43, off
	v_bfe_u32 v43, v42, 16, 1
	v_add3_u32 v51, v42, v43, s89
	v_add_co_u32_e32 v42, vcc, 0x1000, v46
	v_mul_f32_e32 v41, v54, v41
	s_nop 0
	v_addc_co_u32_e32 v43, vcc, 0, v47, vcc
	global_store_short_d16_hi v[42:43], v51, off offset:32
	v_bfe_u32 v42, v41, 16, 1
	v_add3_u32 v41, v41, v42, s89
	v_add_co_u32_e32 v42, vcc, 0x2000, v46
	v_mul_f32_e32 v40, v54, v40
	s_nop 0
	v_addc_co_u32_e32 v43, vcc, 0, v47, vcc
	global_store_short_d16_hi v[42:43], v41, off offset:64
	v_bfe_u32 v41, v40, 16, 1
	v_add3_u32 v42, v40, v41, s89
	v_add_co_u32_e32 v40, vcc, 0x3000, v46
	s_nop 1
	v_addc_co_u32_e32 v41, vcc, 0, v47, vcc
	global_store_short_d16_hi v[40:41], v42, off offset:96
.LBB0_2083:
	s_or_b64 exec, exec, s[12:13]
	v_or_b32_e32 v40, v52, v140
	v_mov_b32_e32 v41, v53
	v_lshl_add_u64 v[40:41], v[40:41], 3, s[78:79]
	s_and_b64 s[38:39], exec, s[4:5]
	s_cbranch_scc0 .Lrope_q_5_2
	s_waitcnt vmcnt(11)
	s_branch .Lrope_w_5_2

.Lrope_w_5_2:
	v_mov_b64_e32 v[40:41], v[180:181]
	v_mov_b64_e32 v[42:43], v[182:183]
	s_mov_b32 s6, 0x3d800000
	s_nop 0
	v_pk_mul_f32 v[46:47], v[36:37], v[40:41] op_sel:[1,1] op_sel_hi:[1,0]
	s_nop 0
	v_pk_fma_f32 v[56:57], v[36:37], v[40:41], v[46:47] op_sel_hi:[0,1,1] neg_lo:[0,0,1] neg_hi:[0,0,1]
	v_pk_fma_f32 v[40:41], v[36:37], v[40:41], v[46:47] op_sel_hi:[0,1,1]
	v_mov_b32_e32 v36, v39
	v_pk_mul_f32 v[36:37], v[36:37], v[42:43] op_sel:[0,1] op_sel_hi:[0,0]
	v_pk_fma_f32 v[46:47], v[38:39], v[42:43], v[36:37] op_sel_hi:[0,1,1] neg_lo:[0,0,1] neg_hi:[0,0,1]
	v_pk_fma_f32 v[38:39], v[38:39], v[42:43], v[36:37] op_sel_hi:[0,1,1]
	v_mov_b32_e32 v47, v39
	v_mov_b32_e32 v57, v41
	v_pk_mul_f32 v[42:43], v[46:47], s[6:7] op_sel_hi:[1,0]
	v_pk_mul_f32 v[58:59], v[56:57], s[6:7] op_sel_hi:[1,0]
	v_cndmask_b32_e64 v37, v46, v42, s[44:45]
	v_cndmask_b32_e64 v36, v39, v43, s[44:45]
	v_cndmask_b32_e64 v39, v56, v58, s[44:45]
	v_cndmask_b32_e64 v38, v41, v59, s[44:45]
	v_cvt_pk_bf16_f32 v40, v39, v38
	v_cvt_pk_bf16_f32 v41, v37, v36
	global_store_dwordx2 v[44:45], v[40:41], off offset:256
	s_and_saveexec_b64 s[12:13], s[4:5]
	s_cbranch_execz .LBB0_2085
	v_readlane_b32 s6, v250, 37
	v_readlane_b32 s7, v250, 38
	v_or_b32_e32 v42, v50, v143
	v_mul_f32_e32 v39, v54, v39
	v_mov_b64_e32 v[40:41], s[6:7]
	v_mad_i64_i32 v[40:41], s[6:7], v42, s9, v[40:41]
	v_bfe_u32 v42, v39, 16, 1
	v_lshl_add_u64 v[40:41], v[48:49], 1, v[40:41]
	v_add3_u32 v39, v39, v42, s89
	v_mul_f32_e32 v38, v54, v38
	global_store_short_d16_hi v[40:41], v39, off
	v_bfe_u32 v39, v38, 16, 1
	v_add3_u32 v42, v38, v39, s89
	v_add_co_u32_e32 v38, vcc, 0x1000, v40
	v_mul_f32_e32 v37, v54, v37
	s_nop 0
	v_addc_co_u32_e32 v39, vcc, 0, v41, vcc
	global_store_short_d16_hi v[38:39], v42, off offset:32
	v_bfe_u32 v38, v37, 16, 1
	v_add3_u32 v37, v37, v38, s89
	v_add_co_u32_e32 v38, vcc, 0x2000, v40
	v_mul_f32_e32 v36, v54, v36
	s_nop 0
	v_addc_co_u32_e32 v39, vcc, 0, v41, vcc
	global_store_short_d16_hi v[38:39], v37, off offset:64
	v_bfe_u32 v37, v36, 16, 1
	v_add3_u32 v38, v36, v37, s89
	v_add_co_u32_e32 v36, vcc, 0x3000, v40
	s_nop 1
	v_addc_co_u32_e32 v37, vcc, 0, v41, vcc
	global_store_short_d16_hi v[36:37], v38, off offset:96
.LBB0_2085:
	s_or_b64 exec, exec, s[12:13]
	v_or_b32_e32 v52, v52, v142
	v_lshl_add_u64 v[36:37], v[52:53], 3, s[78:79]
	s_and_b64 s[38:39], exec, s[4:5]
	s_cbranch_scc0 .Lrope_q_5_3
	s_waitcnt vmcnt(15)
	s_branch .Lrope_w_5_3

.Lrope_w_5_3:
	v_mov_b64_e32 v[36:37], v[184:185]
	v_mov_b64_e32 v[38:39], v[186:187]
	s_mov_b32 s6, 0x3d800000
	s_nop 0
	v_pk_mul_f32 v[40:41], v[32:33], v[36:37] op_sel:[1,1] op_sel_hi:[1,0]
	s_nop 0
	v_pk_fma_f32 v[42:43], v[32:33], v[36:37], v[40:41] op_sel_hi:[0,1,1] neg_lo:[0,0,1] neg_hi:[0,0,1]
	v_pk_fma_f32 v[36:37], v[32:33], v[36:37], v[40:41] op_sel_hi:[0,1,1]
	v_mov_b32_e32 v32, v35
	v_pk_mul_f32 v[32:33], v[32:33], v[38:39] op_sel:[0,1] op_sel_hi:[0,0]
	v_pk_fma_f32 v[40:41], v[34:35], v[38:39], v[32:33] op_sel_hi:[0,1,1] neg_lo:[0,0,1] neg_hi:[0,0,1]
	v_pk_fma_f32 v[34:35], v[34:35], v[38:39], v[32:33] op_sel_hi:[0,1,1]
	v_mov_b32_e32 v41, v35
	v_mov_b32_e32 v43, v37
	v_pk_mul_f32 v[38:39], v[40:41], s[6:7] op_sel_hi:[1,0]
	v_pk_mul_f32 v[46:47], v[42:43], s[6:7] op_sel_hi:[1,0]
	v_cndmask_b32_e64 v33, v40, v38, s[44:45]
	v_cndmask_b32_e64 v32, v35, v39, s[44:45]
	v_cndmask_b32_e64 v35, v42, v46, s[44:45]
	v_cndmask_b32_e64 v34, v37, v47, s[44:45]
	v_cvt_pk_bf16_f32 v36, v35, v34
	v_cvt_pk_bf16_f32 v37, v33, v32
	global_store_dwordx2 v[44:45], v[36:37], off offset:288
	s_and_saveexec_b64 s[12:13], s[4:5]
	s_cbranch_execz .LBB0_2087
	v_readlane_b32 s4, v250, 37
	v_readlane_b32 s5, v250, 38
	v_or_b32_e32 v38, v50, v164
	v_mul_f32_e32 v35, v54, v35
	v_mov_b64_e32 v[36:37], s[4:5]
	v_mad_i64_i32 v[36:37], s[4:5], v38, s9, v[36:37]
	v_bfe_u32 v38, v35, 16, 1
	v_lshl_add_u64 v[36:37], v[48:49], 1, v[36:37]
	v_add3_u32 v35, v35, v38, s89
	v_mul_f32_e32 v34, v54, v34
	global_store_short_d16_hi v[36:37], v35, off
	v_bfe_u32 v35, v34, 16, 1
	v_add3_u32 v38, v34, v35, s89
	v_add_co_u32_e32 v34, vcc, 0x1000, v36
	v_mul_f32_e32 v33, v54, v33
	s_nop 0
	v_addc_co_u32_e32 v35, vcc, 0, v37, vcc
	global_store_short_d16_hi v[34:35], v38, off offset:32
	v_bfe_u32 v34, v33, 16, 1
	v_add3_u32 v33, v33, v34, s89
	v_add_co_u32_e32 v34, vcc, 0x2000, v36
	v_mul_f32_e32 v32, v54, v32
	s_nop 0
	v_addc_co_u32_e32 v35, vcc, 0, v37, vcc
	global_store_short_d16_hi v[34:35], v33, off offset:64
	v_bfe_u32 v33, v32, 16, 1
	v_add3_u32 v34, v32, v33, s89
	v_add_co_u32_e32 v32, vcc, 0x3000, v36
	s_nop 1
	v_addc_co_u32_e32 v33, vcc, 0, v37, vcc
	global_store_short_d16_hi v[32:33], v34, off offset:96

.LBB0_2107:
	s_or_b64 exec, exec, s[12:13]
	v_ashrrev_i32_e32 v37, 31, v36
	v_lshlrev_b64 v[36:37], 7, v[36:37]
	v_cndmask_b32_e64 v37, 0, v37, s[50:51]
	v_cndmask_b32_e64 v36, v234, v36, s[50:51]
	v_ashrrev_i32_e32 v35, 31, v34
	v_lshlrev_b64 v[44:45], 11, v[34:35]
	v_lshl_or_b32 v34, v40, 10, s59
	v_or_b32_e32 v40, v36, v136
	v_mov_b32_e32 v41, v37
	v_lshl_add_u64 v[40:41], v[40:41], 3, s[78:79]
	global_load_dwordx4 v[40:43], v[40:41], off
	v_or_b32_e32 v188, v36, v138
	v_mov_b32_e32 v189, v37
	v_lshl_add_u64 v[188:189], v[188:189], 3, s[78:79]
	global_load_dwordx4 v[176:179], v[188:189], off
	v_or_b32_e32 v188, v36, v140
	v_mov_b32_e32 v189, v37
	v_lshl_add_u64 v[188:189], v[188:189], 3, s[78:79]
	global_load_dwordx4 v[180:183], v[188:189], off
	v_or_b32_e32 v188, v36, v142
	v_mov_b32_e32 v189, v37
	v_lshl_add_u64 v[188:189], v[188:189], 3, s[78:79]
	global_load_dwordx4 v[184:187], v[188:189], off
	s_mov_b32 s6, 0x3d800000
	v_lshlrev_b32_e32 v80, 1, v134
	v_ashrrev_i32_e32 v33, 31, v32
	s_waitcnt vmcnt(3)
	v_pk_mul_f32 v[46:47], v[28:29], v[40:41] op_sel:[1,1] op_sel_hi:[1,0]
	s_nop 0
	v_pk_fma_f32 v[48:49], v[28:29], v[40:41], v[46:47] op_sel_hi:[0,1,1] neg_lo:[0,0,1] neg_hi:[0,0,1]
	v_pk_fma_f32 v[28:29], v[28:29], v[40:41], v[46:47] op_sel_hi:[0,1,1]
	v_mov_b32_e32 v28, v31
	v_pk_mul_f32 v[40:41], v[28:29], v[42:43] op_sel:[0,1] op_sel_hi:[0,0]
	v_pk_fma_f32 v[46:47], v[30:31], v[42:43], v[40:41] op_sel_hi:[0,1,1] neg_lo:[0,0,1] neg_hi:[0,0,1]
	v_pk_fma_f32 v[40:41], v[30:31], v[42:43], v[40:41] op_sel_hi:[0,1,1]
	v_mov_b32_e32 v47, v41
	v_mov_b32_e32 v49, v29
	v_pk_mul_f32 v[42:43], v[46:47], s[6:7] op_sel_hi:[1,0]
	v_pk_mul_f32 v[50:51], v[48:49], s[6:7] op_sel_hi:[1,0]
	s_and_b64 s[6:7], s[44:45], exec
	v_readlane_b32 s6, v252, 32
	v_readlane_b32 s7, v252, 33
	s_cselect_b32 s7, s7, s29
	s_cselect_b32 s6, s6, s28
	v_cndmask_b32_e64 v35, v29, v51, s[44:45]
	v_lshl_add_u64 v[28:29], s[6:7], 0, v[44:45]
	s_lshl_b32 s6, s59, 1
	s_mov_b32 s7, s93
	v_lshl_add_u64 v[28:29], v[28:29], 0, s[6:7]
	v_cndmask_b32_e64 v31, v46, v42, s[44:45]
	v_cndmask_b32_e64 v30, v41, v43, s[44:45]
	v_cndmask_b32_e64 v39, v48, v50, s[44:45]
	v_lshl_add_u64 v[28:29], v[28:29], 0, v[80:81]
	v_cvt_pk_bf16_f32 v40, v39, v35
	v_cvt_pk_bf16_f32 v41, v31, v30
	global_store_dwordx2 v[28:29], v[40:41], off
	s_and_saveexec_b64 s[12:13], s[4:5]
	s_cbranch_execz .LBB0_2109
	v_readlane_b32 s6, v250, 37
	v_readlane_b32 s7, v250, 38
	v_or_b32_e32 v42, v34, v134
	v_mul_f32_e32 v39, v38, v39
	v_mov_b64_e32 v[40:41], s[6:7]
	v_mad_i64_i32 v[40:41], s[6:7], v42, s9, v[40:41]
	v_bfe_u32 v42, v39, 16, 1
	v_lshl_add_u64 v[40:41], v[32:33], 1, v[40:41]
	v_add3_u32 v39, v39, v42, s89
	v_mul_f32_e32 v35, v38, v35
	global_store_short_d16_hi v[40:41], v39, off
	v_bfe_u32 v39, v35, 16, 1
	v_add_co_u32_e32 v42, vcc, 0x1000, v40
	v_add3_u32 v35, v35, v39, s89
	s_nop 0
	v_addc_co_u32_e32 v43, vcc, 0, v41, vcc
	v_mul_f32_e32 v31, v38, v31
	global_store_short_d16_hi v[42:43], v35, off offset:32
	v_bfe_u32 v35, v31, 16, 1
	v_add_co_u32_e32 v42, vcc, 0x2000, v40
	v_add3_u32 v31, v31, v35, s89
	s_nop 0
	v_addc_co_u32_e32 v43, vcc, 0, v41, vcc
	v_mul_f32_e32 v30, v38, v30
	global_store_short_d16_hi v[42:43], v31, off offset:64
	v_bfe_u32 v31, v30, 16, 1
	v_add3_u32 v35, v30, v31, s89
	v_add_co_u32_e32 v30, vcc, 0x3000, v40
	s_nop 1
	v_addc_co_u32_e32 v31, vcc, 0, v41, vcc
	global_store_short_d16_hi v[30:31], v35, off offset:96
.LBB0_2109:
	s_or_b64 exec, exec, s[12:13]
	v_or_b32_e32 v30, v36, v138
	v_mov_b32_e32 v31, v37
	v_lshl_add_u64 v[30:31], v[30:31], 3, s[78:79]
	s_and_b64 s[38:39], exec, s[4:5]
	s_cbranch_scc0 .Lrope_q_6_1
	s_waitcnt vmcnt(7)
	s_branch .Lrope_w_6_1

.Lrope_w_6_1:
	v_mov_b64_e32 v[40:41], v[176:177]
	v_mov_b64_e32 v[42:43], v[178:179]
	s_mov_b32 s6, 0x3d800000
	s_nop 0
	v_pk_mul_f32 v[30:31], v[24:25], v[40:41] op_sel:[1,1] op_sel_hi:[1,0]
	s_nop 0
	v_pk_fma_f32 v[44:45], v[24:25], v[40:41], v[30:31] op_sel_hi:[0,1,1] neg_lo:[0,0,1] neg_hi:[0,0,1]
	v_pk_fma_f32 v[30:31], v[24:25], v[40:41], v[30:31] op_sel_hi:[0,1,1]
	v_mov_b32_e32 v24, v27
	v_pk_mul_f32 v[24:25], v[24:25], v[42:43] op_sel:[0,1] op_sel_hi:[0,0]
	v_pk_fma_f32 v[40:41], v[26:27], v[42:43], v[24:25] op_sel_hi:[0,1,1] neg_lo:[0,0,1] neg_hi:[0,0,1]
	v_pk_fma_f32 v[26:27], v[26:27], v[42:43], v[24:25] op_sel_hi:[0,1,1]
	v_mov_b32_e32 v41, v27
	v_mov_b32_e32 v45, v31
	v_pk_mul_f32 v[42:43], v[40:41], s[6:7] op_sel_hi:[1,0]
	v_pk_mul_f32 v[46:47], v[44:45], s[6:7] op_sel_hi:[1,0]
	v_cndmask_b32_e64 v25, v40, v42, s[44:45]
	v_cndmask_b32_e64 v24, v27, v43, s[44:45]
	v_cndmask_b32_e64 v27, v44, v46, s[44:45]
	v_cndmask_b32_e64 v26, v31, v47, s[44:45]
	v_cvt_pk_bf16_f32 v30, v27, v26
	v_cvt_pk_bf16_f32 v31, v25, v24
	global_store_dwordx2 v[28:29], v[30:31], off offset:32
	s_and_saveexec_b64 s[12:13], s[4:5]
	s_cbranch_execz .LBB0_2111
	v_readlane_b32 s6, v250, 37
	v_readlane_b32 s7, v250, 38
	v_or_b32_e32 v35, v34, v141
	v_mul_f32_e32 v27, v38, v27
	v_mov_b64_e32 v[30:31], s[6:7]
	v_mad_i64_i32 v[30:31], s[6:7], v35, s9, v[30:31]
	v_bfe_u32 v35, v27, 16, 1
	v_lshl_add_u64 v[30:31], v[32:33], 1, v[30:31]
	v_add3_u32 v27, v27, v35, s89
	v_mul_f32_e32 v26, v38, v26
	global_store_short_d16_hi v[30:31], v27, off
	v_bfe_u32 v27, v26, 16, 1
	v_add3_u32 v35, v26, v27, s89
	v_add_co_u32_e32 v26, vcc, 0x1000, v30
	v_mul_f32_e32 v25, v38, v25
	s_nop 0
	v_addc_co_u32_e32 v27, vcc, 0, v31, vcc
	global_store_short_d16_hi v[26:27], v35, off offset:32
	v_bfe_u32 v26, v25, 16, 1
	v_add3_u32 v25, v25, v26, s89
	v_add_co_u32_e32 v26, vcc, 0x2000, v30
	v_mul_f32_e32 v24, v38, v24
	s_nop 0
	v_addc_co_u32_e32 v27, vcc, 0, v31, vcc
	global_store_short_d16_hi v[26:27], v25, off offset:64
	v_bfe_u32 v25, v24, 16, 1
	v_add3_u32 v26, v24, v25, s89
	v_add_co_u32_e32 v24, vcc, 0x3000, v30
	s_nop 1
	v_addc_co_u32_e32 v25, vcc, 0, v31, vcc
	global_store_short_d16_hi v[24:25], v26, off offset:96
.LBB0_2111:
	s_or_b64 exec, exec, s[12:13]
	v_or_b32_e32 v24, v36, v140
	v_mov_b32_e32 v25, v37
	v_lshl_add_u64 v[24:25], v[24:25], 3, s[78:79]
	s_and_b64 s[38:39], exec, s[4:5]
	s_cbranch_scc0 .Lrope_q_6_2
	s_waitcnt vmcnt(11)
	s_branch .Lrope_w_6_2

.Lrope_w_6_2:
	v_mov_b64_e32 v[24:25], v[180:181]
	v_mov_b64_e32 v[26:27], v[182:183]
	s_mov_b32 s6, 0x3d800000
	s_nop 0
	v_pk_mul_f32 v[30:31], v[20:21], v[24:25] op_sel:[1,1] op_sel_hi:[1,0]
	s_nop 0
	v_pk_fma_f32 v[40:41], v[20:21], v[24:25], v[30:31] op_sel_hi:[0,1,1] neg_lo:[0,0,1] neg_hi:[0,0,1]
	v_pk_fma_f32 v[24:25], v[20:21], v[24:25], v[30:31] op_sel_hi:[0,1,1]
	v_mov_b32_e32 v20, v23
	v_pk_mul_f32 v[20:21], v[20:21], v[26:27] op_sel:[0,1] op_sel_hi:[0,0]
	v_pk_fma_f32 v[30:31], v[22:23], v[26:27], v[20:21] op_sel_hi:[0,1,1] neg_lo:[0,0,1] neg_hi:[0,0,1]
	v_pk_fma_f32 v[22:23], v[22:23], v[26:27], v[20:21] op_sel_hi:[0,1,1]
	v_mov_b32_e32 v31, v23
	v_mov_b32_e32 v41, v25
	v_pk_mul_f32 v[26:27], v[30:31], s[6:7] op_sel_hi:[1,0]
	v_pk_mul_f32 v[42:43], v[40:41], s[6:7] op_sel_hi:[1,0]
	v_cndmask_b32_e64 v21, v30, v26, s[44:45]
	v_cndmask_b32_e64 v20, v23, v27, s[44:45]
	v_cndmask_b32_e64 v23, v40, v42, s[44:45]
	v_cndmask_b32_e64 v22, v25, v43, s[44:45]
	v_cvt_pk_bf16_f32 v24, v23, v22
	v_cvt_pk_bf16_f32 v25, v21, v20
	global_store_dwordx2 v[28:29], v[24:25], off offset:256
	s_and_saveexec_b64 s[12:13], s[4:5]
	s_cbranch_execz .LBB0_2113
	v_readlane_b32 s6, v250, 37
	v_readlane_b32 s7, v250, 38
	v_or_b32_e32 v26, v34, v143
	v_mul_f32_e32 v23, v38, v23
	v_mov_b64_e32 v[24:25], s[6:7]
	v_mad_i64_i32 v[24:25], s[6:7], v26, s9, v[24:25]
	v_bfe_u32 v26, v23, 16, 1
	v_lshl_add_u64 v[24:25], v[32:33], 1, v[24:25]
	v_add3_u32 v23, v23, v26, s89
	v_mul_f32_e32 v22, v38, v22
	global_store_short_d16_hi v[24:25], v23, off
	v_bfe_u32 v23, v22, 16, 1
	v_add3_u32 v26, v22, v23, s89
	v_add_co_u32_e32 v22, vcc, 0x1000, v24
	v_mul_f32_e32 v21, v38, v21
	s_nop 0
	v_addc_co_u32_e32 v23, vcc, 0, v25, vcc
	global_store_short_d16_hi v[22:23], v26, off offset:32
	v_bfe_u32 v22, v21, 16, 1
	v_add3_u32 v21, v21, v22, s89
	v_add_co_u32_e32 v22, vcc, 0x2000, v24
	v_mul_f32_e32 v20, v38, v20
	s_nop 0
	v_addc_co_u32_e32 v23, vcc, 0, v25, vcc
	global_store_short_d16_hi v[22:23], v21, off offset:64
	v_bfe_u32 v21, v20, 16, 1
	v_add3_u32 v22, v20, v21, s89
	v_add_co_u32_e32 v20, vcc, 0x3000, v24
	s_nop 1
	v_addc_co_u32_e32 v21, vcc, 0, v25, vcc
	global_store_short_d16_hi v[20:21], v22, off offset:96
.LBB0_2113:
	s_or_b64 exec, exec, s[12:13]
	v_or_b32_e32 v36, v36, v142
	v_lshl_add_u64 v[20:21], v[36:37], 3, s[78:79]
	s_and_b64 s[38:39], exec, s[4:5]
	s_cbranch_scc0 .Lrope_q_6_3
	s_waitcnt vmcnt(15)
	s_branch .Lrope_w_6_3

.Lrope_w_6_3:
	v_mov_b64_e32 v[20:21], v[184:185]
	v_mov_b64_e32 v[22:23], v[186:187]
	s_mov_b32 s6, 0x3d800000
	s_nop 0
	v_pk_mul_f32 v[24:25], v[16:17], v[20:21] op_sel:[1,1] op_sel_hi:[1,0]
	s_nop 0
	v_pk_fma_f32 v[26:27], v[16:17], v[20:21], v[24:25] op_sel_hi:[0,1,1] neg_lo:[0,0,1] neg_hi:[0,0,1]
	v_pk_fma_f32 v[20:21], v[16:17], v[20:21], v[24:25] op_sel_hi:[0,1,1]
	v_mov_b32_e32 v16, v19
	v_pk_mul_f32 v[16:17], v[16:17], v[22:23] op_sel:[0,1] op_sel_hi:[0,0]
	v_pk_fma_f32 v[24:25], v[18:19], v[22:23], v[16:17] op_sel_hi:[0,1,1] neg_lo:[0,0,1] neg_hi:[0,0,1]
	v_pk_fma_f32 v[18:19], v[18:19], v[22:23], v[16:17] op_sel_hi:[0,1,1]
	v_mov_b32_e32 v25, v19
	v_mov_b32_e32 v27, v21
	v_pk_mul_f32 v[22:23], v[24:25], s[6:7] op_sel_hi:[1,0]
	v_pk_mul_f32 v[30:31], v[26:27], s[6:7] op_sel_hi:[1,0]
	v_cndmask_b32_e64 v17, v24, v22, s[44:45]
	v_cndmask_b32_e64 v16, v19, v23, s[44:45]
	v_cndmask_b32_e64 v19, v26, v30, s[44:45]
	v_cndmask_b32_e64 v18, v21, v31, s[44:45]
	v_cvt_pk_bf16_f32 v20, v19, v18
	v_cvt_pk_bf16_f32 v21, v17, v16
	global_store_dwordx2 v[28:29], v[20:21], off offset:288
	s_and_saveexec_b64 s[12:13], s[4:5]
	s_cbranch_execz .LBB0_2115
	v_readlane_b32 s4, v250, 37
	v_readlane_b32 s5, v250, 38
	v_or_b32_e32 v22, v34, v164
	v_mul_f32_e32 v19, v38, v19
	v_mov_b64_e32 v[20:21], s[4:5]
	v_mad_i64_i32 v[20:21], s[4:5], v22, s9, v[20:21]
	v_bfe_u32 v22, v19, 16, 1
	v_lshl_add_u64 v[20:21], v[32:33], 1, v[20:21]
	v_add3_u32 v19, v19, v22, s89
	v_mul_f32_e32 v18, v38, v18
	global_store_short_d16_hi v[20:21], v19, off
	v_bfe_u32 v19, v18, 16, 1
	v_add3_u32 v22, v18, v19, s89
	v_add_co_u32_e32 v18, vcc, 0x1000, v20
	v_mul_f32_e32 v17, v38, v17
	s_nop 0
	v_addc_co_u32_e32 v19, vcc, 0, v21, vcc
	global_store_short_d16_hi v[18:19], v22, off offset:32
	v_bfe_u32 v18, v17, 16, 1
	v_add3_u32 v17, v17, v18, s89
	v_add_co_u32_e32 v18, vcc, 0x2000, v20
	v_mul_f32_e32 v16, v38, v16
	s_nop 0
	v_addc_co_u32_e32 v19, vcc, 0, v21, vcc
	global_store_short_d16_hi v[18:19], v17, off offset:64
	v_bfe_u32 v17, v16, 16, 1
	v_add3_u32 v18, v16, v17, s89
	v_add_co_u32_e32 v16, vcc, 0x3000, v20
	s_nop 1
	v_addc_co_u32_e32 v17, vcc, 0, v21, vcc
	global_store_short_d16_hi v[16:17], v18, off offset:96

.LBB0_2136:
	s_or_b64 exec, exec, s[12:13]
	v_ashrrev_i32_e32 v21, 31, v20
	v_lshlrev_b64 v[20:21], 7, v[20:21]
	v_cndmask_b32_e64 v21, 0, v21, s[50:51]
	v_cndmask_b32_e64 v20, v234, v20, s[50:51]
	v_ashrrev_i32_e32 v19, 31, v18
	v_lshlrev_b64 v[28:29], 11, v[18:19]
	v_lshl_or_b32 v18, v24, 10, s59
	v_or_b32_e32 v24, v20, v136
	v_mov_b32_e32 v25, v21
	v_lshl_add_u64 v[24:25], v[24:25], 3, s[78:79]
	global_load_dwordx4 v[24:27], v[24:25], off
	v_or_b32_e32 v188, v20, v138
	v_mov_b32_e32 v189, v21
	v_lshl_add_u64 v[188:189], v[188:189], 3, s[78:79]
	global_load_dwordx4 v[176:179], v[188:189], off
	v_or_b32_e32 v188, v20, v140
	v_mov_b32_e32 v189, v21
	v_lshl_add_u64 v[188:189], v[188:189], 3, s[78:79]
	global_load_dwordx4 v[180:183], v[188:189], off
	v_or_b32_e32 v188, v20, v142
	v_mov_b32_e32 v189, v21
	v_lshl_add_u64 v[188:189], v[188:189], 3, s[78:79]
	global_load_dwordx4 v[184:187], v[188:189], off
	s_mov_b32 s6, 0x3d800000
	v_lshlrev_b32_e32 v80, 1, v134
	v_ashrrev_i32_e32 v17, 31, v16
	s_waitcnt vmcnt(3)
	v_pk_mul_f32 v[30:31], v[12:13], v[24:25] op_sel:[1,1] op_sel_hi:[1,0]
	s_nop 0
	v_pk_fma_f32 v[32:33], v[12:13], v[24:25], v[30:31] op_sel_hi:[0,1,1] neg_lo:[0,0,1] neg_hi:[0,0,1]
	v_pk_fma_f32 v[12:13], v[12:13], v[24:25], v[30:31] op_sel_hi:[0,1,1]
	v_mov_b32_e32 v12, v15
	v_pk_mul_f32 v[24:25], v[12:13], v[26:27] op_sel:[0,1] op_sel_hi:[0,0]
	v_pk_fma_f32 v[30:31], v[14:15], v[26:27], v[24:25] op_sel_hi:[0,1,1] neg_lo:[0,0,1] neg_hi:[0,0,1]
	v_pk_fma_f32 v[24:25], v[14:15], v[26:27], v[24:25] op_sel_hi:[0,1,1]
	v_mov_b32_e32 v31, v25
	v_mov_b32_e32 v33, v13
	v_pk_mul_f32 v[26:27], v[30:31], s[6:7] op_sel_hi:[1,0]
	v_pk_mul_f32 v[34:35], v[32:33], s[6:7] op_sel_hi:[1,0]
	s_and_b64 s[6:7], s[44:45], exec
	v_readlane_b32 s6, v252, 32
	v_readlane_b32 s7, v252, 33
	s_cselect_b32 s7, s7, s29
	s_cselect_b32 s6, s6, s28
	v_cndmask_b32_e64 v19, v13, v35, s[44:45]
	v_lshl_add_u64 v[12:13], s[6:7], 0, v[28:29]
	s_lshl_b32 s92, s59, 1
	v_lshl_add_u64 v[12:13], v[12:13], 0, s[92:93]
	v_cndmask_b32_e64 v15, v30, v26, s[44:45]
	v_cndmask_b32_e64 v14, v25, v27, s[44:45]
	v_cndmask_b32_e64 v23, v32, v34, s[44:45]
	v_lshl_add_u64 v[12:13], v[12:13], 0, v[80:81]
	v_cvt_pk_bf16_f32 v24, v23, v19
	v_cvt_pk_bf16_f32 v25, v15, v14
	global_store_dwordx2 v[12:13], v[24:25], off
	s_and_saveexec_b64 s[12:13], s[4:5]
	s_cbranch_execz .LBB0_2138
	v_readlane_b32 s6, v250, 37
	v_readlane_b32 s7, v250, 38
	v_or_b32_e32 v26, v18, v134
	v_mul_f32_e32 v23, v22, v23
	v_mov_b64_e32 v[24:25], s[6:7]
	v_mad_i64_i32 v[24:25], s[6:7], v26, s9, v[24:25]
	v_bfe_u32 v26, v23, 16, 1
	v_lshl_add_u64 v[24:25], v[16:17], 1, v[24:25]
	v_add3_u32 v23, v23, v26, s89
	v_mul_f32_e32 v19, v22, v19
	global_store_short_d16_hi v[24:25], v23, off
	v_bfe_u32 v23, v19, 16, 1
	v_add_co_u32_e32 v26, vcc, 0x1000, v24
	v_add3_u32 v19, v19, v23, s89
	s_nop 0
	v_addc_co_u32_e32 v27, vcc, 0, v25, vcc
	v_mul_f32_e32 v15, v22, v15
	global_store_short_d16_hi v[26:27], v19, off offset:32
	v_bfe_u32 v19, v15, 16, 1
	v_add_co_u32_e32 v26, vcc, 0x2000, v24
	v_add3_u32 v15, v15, v19, s89
	s_nop 0
	v_addc_co_u32_e32 v27, vcc, 0, v25, vcc
	v_mul_f32_e32 v14, v22, v14
	global_store_short_d16_hi v[26:27], v15, off offset:64
	v_bfe_u32 v15, v14, 16, 1
	v_add3_u32 v19, v14, v15, s89
	v_add_co_u32_e32 v14, vcc, 0x3000, v24
	s_nop 1
	v_addc_co_u32_e32 v15, vcc, 0, v25, vcc
	global_store_short_d16_hi v[14:15], v19, off offset:96
.LBB0_2138:
	s_or_b64 exec, exec, s[12:13]
	v_or_b32_e32 v14, v20, v138
	v_mov_b32_e32 v15, v21
	v_lshl_add_u64 v[14:15], v[14:15], 3, s[78:79]
	s_and_b64 s[38:39], exec, s[4:5]
	s_cbranch_scc0 .Lrope_q_7_1
	s_waitcnt vmcnt(7)
	s_branch .Lrope_w_7_1

.Lrope_w_7_1:
	v_mov_b64_e32 v[24:25], v[176:177]
	v_mov_b64_e32 v[26:27], v[178:179]
	s_mov_b32 s6, 0x3d800000
	s_nop 0
	v_pk_mul_f32 v[14:15], v[8:9], v[24:25] op_sel:[1,1] op_sel_hi:[1,0]
	s_nop 0
	v_pk_fma_f32 v[28:29], v[8:9], v[24:25], v[14:15] op_sel_hi:[0,1,1] neg_lo:[0,0,1] neg_hi:[0,0,1]
	v_pk_fma_f32 v[14:15], v[8:9], v[24:25], v[14:15] op_sel_hi:[0,1,1]
	v_mov_b32_e32 v8, v11
	v_pk_mul_f32 v[8:9], v[8:9], v[26:27] op_sel:[0,1] op_sel_hi:[0,0]
	v_pk_fma_f32 v[24:25], v[10:11], v[26:27], v[8:9] op_sel_hi:[0,1,1] neg_lo:[0,0,1] neg_hi:[0,0,1]
	v_pk_fma_f32 v[10:11], v[10:11], v[26:27], v[8:9] op_sel_hi:[0,1,1]
	v_mov_b32_e32 v25, v11
	v_mov_b32_e32 v29, v15
	v_pk_mul_f32 v[26:27], v[24:25], s[6:7] op_sel_hi:[1,0]
	v_pk_mul_f32 v[30:31], v[28:29], s[6:7] op_sel_hi:[1,0]
	v_cndmask_b32_e64 v9, v24, v26, s[44:45]
	v_cndmask_b32_e64 v8, v11, v27, s[44:45]
	v_cndmask_b32_e64 v11, v28, v30, s[44:45]
	v_cndmask_b32_e64 v10, v15, v31, s[44:45]
	v_cvt_pk_bf16_f32 v14, v11, v10
	v_cvt_pk_bf16_f32 v15, v9, v8
	global_store_dwordx2 v[12:13], v[14:15], off offset:32
	s_and_saveexec_b64 s[12:13], s[4:5]
	s_cbranch_execz .LBB0_2140
	v_readlane_b32 s6, v250, 37
	v_readlane_b32 s7, v250, 38
	v_or_b32_e32 v19, v18, v141
	v_mul_f32_e32 v11, v22, v11
	v_mov_b64_e32 v[14:15], s[6:7]
	v_mad_i64_i32 v[14:15], s[6:7], v19, s9, v[14:15]
	v_bfe_u32 v19, v11, 16, 1
	v_lshl_add_u64 v[14:15], v[16:17], 1, v[14:15]
	v_add3_u32 v11, v11, v19, s89
	v_mul_f32_e32 v10, v22, v10
	global_store_short_d16_hi v[14:15], v11, off
	v_bfe_u32 v11, v10, 16, 1
	v_add3_u32 v19, v10, v11, s89
	v_add_co_u32_e32 v10, vcc, 0x1000, v14
	v_mul_f32_e32 v9, v22, v9
	s_nop 0
	v_addc_co_u32_e32 v11, vcc, 0, v15, vcc
	global_store_short_d16_hi v[10:11], v19, off offset:32
	v_bfe_u32 v10, v9, 16, 1
	v_add3_u32 v9, v9, v10, s89
	v_add_co_u32_e32 v10, vcc, 0x2000, v14
	v_mul_f32_e32 v8, v22, v8
	s_nop 0
	v_addc_co_u32_e32 v11, vcc, 0, v15, vcc
	global_store_short_d16_hi v[10:11], v9, off offset:64
	v_bfe_u32 v9, v8, 16, 1
	v_add3_u32 v10, v8, v9, s89
	v_add_co_u32_e32 v8, vcc, 0x3000, v14
	s_nop 1
	v_addc_co_u32_e32 v9, vcc, 0, v15, vcc
	global_store_short_d16_hi v[8:9], v10, off offset:96
.LBB0_2140:
	s_or_b64 exec, exec, s[12:13]
	v_or_b32_e32 v8, v20, v140
	v_mov_b32_e32 v9, v21
	v_lshl_add_u64 v[8:9], v[8:9], 3, s[78:79]
	s_and_b64 s[38:39], exec, s[4:5]
	s_cbranch_scc0 .Lrope_q_7_2
	s_waitcnt vmcnt(11)
	s_branch .Lrope_w_7_2

.Lrope_w_7_2:
	v_mov_b64_e32 v[8:9], v[180:181]
	v_mov_b64_e32 v[10:11], v[182:183]
	s_mov_b32 s6, 0x3d800000
	s_nop 0
	v_pk_mul_f32 v[14:15], v[4:5], v[8:9] op_sel:[1,1] op_sel_hi:[1,0]
	s_nop 0
	v_pk_fma_f32 v[24:25], v[4:5], v[8:9], v[14:15] op_sel_hi:[0,1,1] neg_lo:[0,0,1] neg_hi:[0,0,1]
	v_pk_fma_f32 v[8:9], v[4:5], v[8:9], v[14:15] op_sel_hi:[0,1,1]
	v_mov_b32_e32 v4, v7
	v_pk_mul_f32 v[4:5], v[4:5], v[10:11] op_sel:[0,1] op_sel_hi:[0,0]
	v_pk_fma_f32 v[14:15], v[6:7], v[10:11], v[4:5] op_sel_hi:[0,1,1] neg_lo:[0,0,1] neg_hi:[0,0,1]
	v_pk_fma_f32 v[6:7], v[6:7], v[10:11], v[4:5] op_sel_hi:[0,1,1]
	v_mov_b32_e32 v15, v7
	v_mov_b32_e32 v25, v9
	v_pk_mul_f32 v[10:11], v[14:15], s[6:7] op_sel_hi:[1,0]
	v_pk_mul_f32 v[26:27], v[24:25], s[6:7] op_sel_hi:[1,0]
	v_cndmask_b32_e64 v5, v14, v10, s[44:45]
	v_cndmask_b32_e64 v4, v7, v11, s[44:45]
	v_cndmask_b32_e64 v7, v24, v26, s[44:45]
	v_cndmask_b32_e64 v6, v9, v27, s[44:45]
	v_cvt_pk_bf16_f32 v8, v7, v6
	v_cvt_pk_bf16_f32 v9, v5, v4
	global_store_dwordx2 v[12:13], v[8:9], off offset:256
	s_and_saveexec_b64 s[12:13], s[4:5]
	s_cbranch_execz .LBB0_2142
	v_readlane_b32 s6, v250, 37
	v_readlane_b32 s7, v250, 38
	v_or_b32_e32 v10, v18, v143
	v_mul_f32_e32 v7, v22, v7
	v_mov_b64_e32 v[8:9], s[6:7]
	v_mad_i64_i32 v[8:9], s[6:7], v10, s9, v[8:9]
	v_bfe_u32 v10, v7, 16, 1
	v_lshl_add_u64 v[8:9], v[16:17], 1, v[8:9]
	v_add3_u32 v7, v7, v10, s89
	v_mul_f32_e32 v6, v22, v6
	global_store_short_d16_hi v[8:9], v7, off
	v_bfe_u32 v7, v6, 16, 1
	v_add3_u32 v10, v6, v7, s89
	v_add_co_u32_e32 v6, vcc, 0x1000, v8
	v_mul_f32_e32 v5, v22, v5
	s_nop 0
	v_addc_co_u32_e32 v7, vcc, 0, v9, vcc
	global_store_short_d16_hi v[6:7], v10, off offset:32
	v_bfe_u32 v6, v5, 16, 1
	v_add3_u32 v5, v5, v6, s89
	v_add_co_u32_e32 v6, vcc, 0x2000, v8
	v_mul_f32_e32 v4, v22, v4
	s_nop 0
	v_addc_co_u32_e32 v7, vcc, 0, v9, vcc
	global_store_short_d16_hi v[6:7], v5, off offset:64
	v_bfe_u32 v5, v4, 16, 1
	v_add3_u32 v6, v4, v5, s89
	v_add_co_u32_e32 v4, vcc, 0x3000, v8
	s_nop 1
	v_addc_co_u32_e32 v5, vcc, 0, v9, vcc
	global_store_short_d16_hi v[4:5], v6, off offset:96
.LBB0_2142:
	s_or_b64 exec, exec, s[12:13]
	v_or_b32_e32 v20, v20, v142
	v_lshl_add_u64 v[4:5], v[20:21], 3, s[78:79]
	s_and_b64 s[38:39], exec, s[4:5]
	s_cbranch_scc0 .Lrope_q_7_3
	s_waitcnt vmcnt(15)
	s_branch .Lrope_w_7_3

.Lrope_w_7_3:
	v_mov_b64_e32 v[4:5], v[184:185]
	v_mov_b64_e32 v[6:7], v[186:187]
	s_mov_b32 s6, 0x3d800000
	s_nop 0
	v_pk_mul_f32 v[8:9], v[0:1], v[4:5] op_sel:[1,1] op_sel_hi:[1,0]
	s_nop 0
	v_pk_fma_f32 v[10:11], v[0:1], v[4:5], v[8:9] op_sel_hi:[0,1,1] neg_lo:[0,0,1] neg_hi:[0,0,1]
	v_pk_fma_f32 v[4:5], v[0:1], v[4:5], v[8:9] op_sel_hi:[0,1,1]
	v_mov_b32_e32 v0, v3
	v_pk_mul_f32 v[0:1], v[0:1], v[6:7] op_sel:[0,1] op_sel_hi:[0,0]
	v_pk_fma_f32 v[8:9], v[2:3], v[6:7], v[0:1] op_sel_hi:[0,1,1] neg_lo:[0,0,1] neg_hi:[0,0,1]
	v_pk_fma_f32 v[2:3], v[2:3], v[6:7], v[0:1] op_sel_hi:[0,1,1]
	v_mov_b32_e32 v9, v3
	v_mov_b32_e32 v11, v5
	v_pk_mul_f32 v[6:7], v[8:9], s[6:7] op_sel_hi:[1,0]
	v_pk_mul_f32 v[14:15], v[10:11], s[6:7] op_sel_hi:[1,0]
	v_cndmask_b32_e64 v1, v8, v6, s[44:45]
	v_cndmask_b32_e64 v0, v3, v7, s[44:45]
	v_cndmask_b32_e64 v3, v10, v14, s[44:45]
	v_cndmask_b32_e64 v2, v5, v15, s[44:45]
	v_cvt_pk_bf16_f32 v4, v3, v2
	v_cvt_pk_bf16_f32 v5, v1, v0
	global_store_dwordx2 v[12:13], v[4:5], off offset:288
	s_and_saveexec_b64 s[12:13], s[4:5]
	s_cbranch_execz .LBB0_2144
	v_readlane_b32 s4, v250, 37
	v_readlane_b32 s5, v250, 38
	v_or_b32_e32 v6, v18, v164
	v_mul_f32_e32 v3, v22, v3
	v_mov_b64_e32 v[4:5], s[4:5]
	v_mad_i64_i32 v[4:5], s[4:5], v6, s9, v[4:5]
	v_bfe_u32 v6, v3, 16, 1
	v_lshl_add_u64 v[4:5], v[16:17], 1, v[4:5]
	v_add3_u32 v3, v3, v6, s89
	v_mul_f32_e32 v2, v22, v2
	global_store_short_d16_hi v[4:5], v3, off
	v_bfe_u32 v3, v2, 16, 1
	v_add3_u32 v6, v2, v3, s89
	v_add_co_u32_e32 v2, vcc, 0x1000, v4
	v_mul_f32_e32 v1, v22, v1
	s_nop 0
	v_addc_co_u32_e32 v3, vcc, 0, v5, vcc
	global_store_short_d16_hi v[2:3], v6, off offset:32
	v_bfe_u32 v2, v1, 16, 1
	v_add3_u32 v1, v1, v2, s89
	v_add_co_u32_e32 v2, vcc, 0x2000, v4
	v_mul_f32_e32 v0, v22, v0
	s_nop 0
	v_addc_co_u32_e32 v3, vcc, 0, v5, vcc
	global_store_short_d16_hi v[2:3], v1, off offset:64
	v_bfe_u32 v1, v0, 16, 1
	v_add3_u32 v2, v0, v1, s89
	v_add_co_u32_e32 v0, vcc, 0x3000, v4
	s_nop 1
	v_addc_co_u32_e32 v1, vcc, 0, v5, vcc
	global_store_short_d16_hi v[0:1], v2, off offset:96

.LBB0_3018:
	v_readlane_b32 s12, v252, 30
	v_readlane_b32 s13, v252, 31
	v_mov_b32_e32 v0, v226
	s_andn2_b64 vcc, exec, s[12:13]
	s_mov_b32 s26, 0xb606000
	s_cbranch_vccnz .LBB0_3017
	v_readlane_b32 s14, v250, 6
	s_cmp_gt_u32 s14, 0xff
	s_cbranch_scc1 .Lslab_skip_a
	v_and_b32_e32 v2, 63, v226
	v_lshlrev_b32_e32 v2, 4, v2
	v_lshl_add_u32 v60, s14, 13, v2
	v_mov_b32_e32 v61, 0
	v_lshl_add_u32 v2, s14, 12, v2
	v_mov_b32_e32 v3, 0
	v_readlane_b32 s18, v254, 55
	s_cmp_eq_u32 s18, 1
	s_cbranch_scc1 .Lslab_a_l1
	v_readlane_b32 s14, v250, 15
	v_readlane_b32 s18, v250, 16
	s_add_u32 s12, s14, 0xb506000
	s_addc_u32 s13, s18, 0
	v_lshl_add_u64 v[4:5], s[12:13], 0, v[2:3]
	global_load_dwordx4 v[8:11], v[4:5], off sc1
	global_load_dwordx4 v[12:15], v[4:5], off offset:1024 sc1
	global_load_dwordx4 v[16:19], v[4:5], off offset:2048 sc1
	global_load_dwordx4 v[20:23], v[4:5], off offset:3072 sc1
	v_readlane_b32 s14, v250, 15
	v_readlane_b32 s18, v250, 16
	s_add_u32 s12, s14, 0x284e6000
	s_addc_u32 s13, s18, 0
	global_load_dword v6, v3, s[12:13] sc1
	v_readlane_b32 s14, v250, 15
	v_readlane_b32 s18, v250, 16
	s_add_u32 s12, s14, 0x274e6000
	s_addc_u32 s13, s18, 0
	v_lshl_add_u64 v[24:25], s[12:13], 0, v[2:3]
	s_mov_b64 s[12:13], 0x100000
	v_lshl_add_u64 v[26:27], v[24:25], 0, s[12:13]
	v_lshl_add_u64 v[78:79], v[26:27], 0, s[12:13]
	v_lshl_add_u64 v[98:99], v[78:79], 0, s[12:13]
	s_mov_b64 s[12:13], 0x400000
	s_waitcnt vmcnt(0)
	v_readfirstlane_b32 s18, v6
	s_lshr_b32 s18, s18, 2
.Lslab_loop_an:
	global_load_dwordx4 v[28:31], v[24:25], off
	global_load_dwordx4 v[32:35], v[24:25], off offset:1024
	global_load_dwordx4 v[36:39], v[24:25], off offset:2048
	global_load_dwordx4 v[40:43], v[24:25], off offset:3072
	global_load_dwordx4 v[44:47], v[26:27], off
	global_load_dwordx4 v[48:51], v[26:27], off offset:1024
	global_load_dwordx4 v[52:55], v[26:27], off offset:2048
	global_load_dwordx4 v[56:59], v[26:27], off offset:3072
	global_load_dwordx4 v[62:65], v[78:79], off
	global_load_dwordx4 v[66:69], v[78:79], off offset:1024
	global_load_dwordx4 v[70:73], v[78:79], off offset:2048
	global_load_dwordx4 v[74:77], v[78:79], off offset:3072
	global_load_dwordx4 v[82:85], v[98:99], off
	global_load_dwordx4 v[86:89], v[98:99], off offset:1024
	global_load_dwordx4 v[90:93], v[98:99], off offset:2048
	global_load_dwordx4 v[94:97], v[98:99], off offset:3072
	v_lshl_add_u64 v[24:25], v[24:25], 0, s[12:13]
	v_lshl_add_u64 v[26:27], v[26:27], 0, s[12:13]
	v_lshl_add_u64 v[78:79], v[78:79], 0, s[12:13]
	v_lshl_add_u64 v[98:99], v[98:99], 0, s[12:13]
	s_waitcnt vmcnt(12)
	v_pk_add_f32 v[8:9], v[8:9], v[28:29]
	v_pk_add_f32 v[10:11], v[10:11], v[30:31]
	v_pk_add_f32 v[12:13], v[12:13], v[32:33]
	v_pk_add_f32 v[14:15], v[14:15], v[34:35]
	v_pk_add_f32 v[16:17], v[16:17], v[36:37]
	v_pk_add_f32 v[18:19], v[18:19], v[38:39]
	v_pk_add_f32 v[20:21], v[20:21], v[40:41]
	v_pk_add_f32 v[22:23], v[22:23], v[42:43]
	s_waitcnt vmcnt(8)
	v_pk_add_f32 v[8:9], v[8:9], v[44:45]
	v_pk_add_f32 v[10:11], v[10:11], v[46:47]
	v_pk_add_f32 v[12:13], v[12:13], v[48:49]
	v_pk_add_f32 v[14:15], v[14:15], v[50:51]
	v_pk_add_f32 v[16:17], v[16:17], v[52:53]
	v_pk_add_f32 v[18:19], v[18:19], v[54:55]
	v_pk_add_f32 v[20:21], v[20:21], v[56:57]
	v_pk_add_f32 v[22:23], v[22:23], v[58:59]
	s_waitcnt vmcnt(4)
	v_pk_add_f32 v[8:9], v[8:9], v[62:63]
	v_pk_add_f32 v[10:11], v[10:11], v[64:65]
	v_pk_add_f32 v[12:13], v[12:13], v[66:67]
	v_pk_add_f32 v[14:15], v[14:15], v[68:69]
	v_pk_add_f32 v[16:17], v[16:17], v[70:71]
	v_pk_add_f32 v[18:19], v[18:19], v[72:73]
	v_pk_add_f32 v[20:21], v[20:21], v[74:75]
	v_pk_add_f32 v[22:23], v[22:23], v[76:77]
	s_waitcnt vmcnt(0)
	v_pk_add_f32 v[8:9], v[8:9], v[82:83]
	v_pk_add_f32 v[10:11], v[10:11], v[84:85]
	v_pk_add_f32 v[12:13], v[12:13], v[86:87]
	v_pk_add_f32 v[14:15], v[14:15], v[88:89]
	v_pk_add_f32 v[16:17], v[16:17], v[90:91]
	v_pk_add_f32 v[18:19], v[18:19], v[92:93]
	v_pk_add_f32 v[20:21], v[20:21], v[94:95]
	v_pk_add_f32 v[22:23], v[22:23], v[96:97]
	s_add_i32 s18, s18, -1
	s_cmp_lg_u32 s18, 0
	s_cbranch_scc1 .Lslab_loop_an
	v_readlane_b32 s14, v250, 15
	v_readlane_b32 s18, v250, 16
	s_add_u32 s12, s14, 0xb506000
	s_addc_u32 s13, s18, 0
	v_lshl_add_u64 v[4:5], s[12:13], 0, v[2:3]
	global_store_dwordx4 v[4:5], v[8:11], off
	global_store_dwordx4 v[4:5], v[12:15], off offset:1024
	global_store_dwordx4 v[4:5], v[16:19], off offset:2048
	global_store_dwordx4 v[4:5], v[20:23], off offset:3072
	s_branch .Lslab_done_a
.Lslab_a_l1:
	v_readlane_b32 s14, v250, 13
	v_readlane_b32 s18, v250, 14
	s_add_u32 s12, s14, 0x1000
	s_addc_u32 s13, s18, 0
	v_lshl_add_u64 v[4:5], s[12:13], 0, v[60:61]
	global_load_dwordx4 v[8:11], v[4:5], off sc1
	global_load_dwordx4 v[12:15], v[4:5], off offset:1024 sc1
	global_load_dwordx4 v[16:19], v[4:5], off offset:2048 sc1
	global_load_dwordx4 v[20:23], v[4:5], off offset:3072 sc1
	v_readlane_b32 s14, v250, 15
	v_readlane_b32 s18, v250, 16
	s_add_u32 s12, s14, 0x284e6000
	s_addc_u32 s13, s18, 0
	global_load_dword v6, v3, s[12:13] sc1
	v_readlane_b32 s14, v250, 15
	v_readlane_b32 s18, v250, 16
	s_add_u32 s12, s14, 0x274e6000
	s_addc_u32 s13, s18, 0
	v_lshl_add_u64 v[24:25], s[12:13], 0, v[2:3]
	s_mov_b64 s[12:13], 0x100000
	v_lshl_add_u64 v[26:27], v[24:25], 0, s[12:13]
	v_lshl_add_u64 v[78:79], v[26:27], 0, s[12:13]
	v_lshl_add_u64 v[98:99], v[78:79], 0, s[12:13]
	s_mov_b64 s[12:13], 0x400000
	s_waitcnt vmcnt(0)
	v_readfirstlane_b32 s18, v6
	s_lshr_b32 s18, s18, 2
.Lslab_loop_as:
	global_load_dwordx4 v[28:31], v[24:25], off
	global_load_dwordx4 v[32:35], v[24:25], off offset:1024
	global_load_dwordx4 v[36:39], v[24:25], off offset:2048
	global_load_dwordx4 v[40:43], v[24:25], off offset:3072
	global_load_dwordx4 v[44:47], v[26:27], off
	global_load_dwordx4 v[48:51], v[26:27], off offset:1024
	global_load_dwordx4 v[52:55], v[26:27], off offset:2048
	global_load_dwordx4 v[56:59], v[26:27], off offset:3072
	global_load_dwordx4 v[62:65], v[78:79], off
	global_load_dwordx4 v[66:69], v[78:79], off offset:1024
	global_load_dwordx4 v[70:73], v[78:79], off offset:2048
	global_load_dwordx4 v[74:77], v[78:79], off offset:3072
	global_load_dwordx4 v[82:85], v[98:99], off
	global_load_dwordx4 v[86:89], v[98:99], off offset:1024
	global_load_dwordx4 v[90:93], v[98:99], off offset:2048
	global_load_dwordx4 v[94:97], v[98:99], off offset:3072
	v_lshl_add_u64 v[24:25], v[24:25], 0, s[12:13]
	v_lshl_add_u64 v[26:27], v[26:27], 0, s[12:13]
	v_lshl_add_u64 v[78:79], v[78:79], 0, s[12:13]
	v_lshl_add_u64 v[98:99], v[98:99], 0, s[12:13]
	s_waitcnt vmcnt(12)
	v_pk_add_f32 v[8:9], v[8:9], v[28:29]
	v_pk_add_f32 v[10:11], v[10:11], v[30:31]
	v_pk_add_f32 v[12:13], v[12:13], v[32:33]
	v_pk_add_f32 v[14:15], v[14:15], v[34:35]
	v_pk_add_f32 v[16:17], v[16:17], v[36:37]
	v_pk_add_f32 v[18:19], v[18:19], v[38:39]
	v_pk_add_f32 v[20:21], v[20:21], v[40:41]
	v_pk_add_f32 v[22:23], v[22:23], v[42:43]
	s_waitcnt vmcnt(8)
	v_pk_add_f32 v[8:9], v[8:9], v[44:45]
	v_pk_add_f32 v[10:11], v[10:11], v[46:47]
	v_pk_add_f32 v[12:13], v[12:13], v[48:49]
	v_pk_add_f32 v[14:15], v[14:15], v[50:51]
	v_pk_add_f32 v[16:17], v[16:17], v[52:53]
	v_pk_add_f32 v[18:19], v[18:19], v[54:55]
	v_pk_add_f32 v[20:21], v[20:21], v[56:57]
	v_pk_add_f32 v[22:23], v[22:23], v[58:59]
	s_waitcnt vmcnt(4)
	v_pk_add_f32 v[8:9], v[8:9], v[62:63]
	v_pk_add_f32 v[10:11], v[10:11], v[64:65]
	v_pk_add_f32 v[12:13], v[12:13], v[66:67]
	v_pk_add_f32 v[14:15], v[14:15], v[68:69]
	v_pk_add_f32 v[16:17], v[16:17], v[70:71]
	v_pk_add_f32 v[18:19], v[18:19], v[72:73]
	v_pk_add_f32 v[20:21], v[20:21], v[74:75]
	v_pk_add_f32 v[22:23], v[22:23], v[76:77]
	s_waitcnt vmcnt(0)
	v_pk_add_f32 v[8:9], v[8:9], v[82:83]
	v_pk_add_f32 v[10:11], v[10:11], v[84:85]
	v_pk_add_f32 v[12:13], v[12:13], v[86:87]
	v_pk_add_f32 v[14:15], v[14:15], v[88:89]
	v_pk_add_f32 v[16:17], v[16:17], v[90:91]
	v_pk_add_f32 v[18:19], v[18:19], v[92:93]
	v_pk_add_f32 v[20:21], v[20:21], v[94:95]
	v_pk_add_f32 v[22:23], v[22:23], v[96:97]
	s_add_i32 s18, s18, -1
	s_cmp_lg_u32 s18, 0
	s_cbranch_scc1 .Lslab_loop_as
	v_readlane_b32 s14, v250, 15
	v_readlane_b32 s18, v250, 16
	s_add_u32 s12, s14, 0xb506000
	s_addc_u32 s13, s18, 0
	v_lshl_add_u64 v[4:5], s[12:13], 0, v[2:3]
	global_store_dwordx4 v[4:5], v[8:11], off
	global_store_dwordx4 v[4:5], v[12:15], off offset:1024
	global_store_dwordx4 v[4:5], v[16:19], off offset:2048
	global_store_dwordx4 v[4:5], v[20:23], off offset:3072

.LBB0_3452:
	v_readlane_b32 s26, v250, 6
	s_cmp_gt_u32 s26, 0xff
	s_cbranch_scc1 .Lslab_skip_b
	v_and_b32_e32 v2, 63, v226
	v_lshlrev_b32_e32 v2, 4, v2
	v_lshl_add_u32 v60, s26, 13, v2
	v_mov_b32_e32 v61, 0
	v_lshl_add_u32 v2, s26, 12, v2
	v_mov_b32_e32 v3, 0
	v_readlane_b32 s27, v254, 55
	s_cmp_eq_u32 s27, 0
	s_cbranch_scc1 .Lslab_b_l0
	v_readlane_b32 s26, v250, 15
	v_readlane_b32 s27, v250, 16
	s_add_u32 s18, s26, 0xb506000
	s_addc_u32 s19, s27, 0
	v_lshl_add_u64 v[4:5], s[18:19], 0, v[2:3]
	global_load_dwordx4 v[8:11], v[4:5], off sc1
	global_load_dwordx4 v[12:15], v[4:5], off offset:1024 sc1
	global_load_dwordx4 v[16:19], v[4:5], off offset:2048 sc1
	global_load_dwordx4 v[20:23], v[4:5], off offset:3072 sc1
	v_readlane_b32 s26, v250, 15
	v_readlane_b32 s27, v250, 16
	s_add_u32 s18, s26, 0x284e6000
	s_addc_u32 s19, s27, 0
	global_load_dword v6, v3, s[18:19] sc1
	v_readlane_b32 s26, v250, 15
	v_readlane_b32 s27, v250, 16
	s_add_u32 s18, s26, 0x274e6000
	s_addc_u32 s19, s27, 0
	v_lshl_add_u64 v[24:25], s[18:19], 0, v[2:3]
	s_mov_b64 s[18:19], 0x100000
	v_lshl_add_u64 v[26:27], v[24:25], 0, s[18:19]
	v_lshl_add_u64 v[78:79], v[26:27], 0, s[18:19]
	v_lshl_add_u64 v[98:99], v[78:79], 0, s[18:19]
	s_mov_b64 s[18:19], 0x400000
	s_waitcnt vmcnt(0)
	v_readfirstlane_b32 s27, v6
	s_lshr_b32 s27, s27, 2
.Lslab_loop_bn:
	global_load_dwordx4 v[28:31], v[24:25], off
	global_load_dwordx4 v[32:35], v[24:25], off offset:1024
	global_load_dwordx4 v[36:39], v[24:25], off offset:2048
	global_load_dwordx4 v[40:43], v[24:25], off offset:3072
	global_load_dwordx4 v[44:47], v[26:27], off
	global_load_dwordx4 v[48:51], v[26:27], off offset:1024
	global_load_dwordx4 v[52:55], v[26:27], off offset:2048
	global_load_dwordx4 v[56:59], v[26:27], off offset:3072
	global_load_dwordx4 v[62:65], v[78:79], off
	global_load_dwordx4 v[66:69], v[78:79], off offset:1024
	global_load_dwordx4 v[70:73], v[78:79], off offset:2048
	global_load_dwordx4 v[74:77], v[78:79], off offset:3072
	global_load_dwordx4 v[82:85], v[98:99], off
	global_load_dwordx4 v[86:89], v[98:99], off offset:1024
	global_load_dwordx4 v[90:93], v[98:99], off offset:2048
	global_load_dwordx4 v[94:97], v[98:99], off offset:3072
	v_lshl_add_u64 v[24:25], v[24:25], 0, s[18:19]
	v_lshl_add_u64 v[26:27], v[26:27], 0, s[18:19]
	v_lshl_add_u64 v[78:79], v[78:79], 0, s[18:19]
	v_lshl_add_u64 v[98:99], v[98:99], 0, s[18:19]
	s_waitcnt vmcnt(12)
	v_pk_add_f32 v[8:9], v[8:9], v[28:29]
	v_pk_add_f32 v[10:11], v[10:11], v[30:31]
	v_pk_add_f32 v[12:13], v[12:13], v[32:33]
	v_pk_add_f32 v[14:15], v[14:15], v[34:35]
	v_pk_add_f32 v[16:17], v[16:17], v[36:37]
	v_pk_add_f32 v[18:19], v[18:19], v[38:39]
	v_pk_add_f32 v[20:21], v[20:21], v[40:41]
	v_pk_add_f32 v[22:23], v[22:23], v[42:43]
	s_waitcnt vmcnt(8)
	v_pk_add_f32 v[8:9], v[8:9], v[44:45]
	v_pk_add_f32 v[10:11], v[10:11], v[46:47]
	v_pk_add_f32 v[12:13], v[12:13], v[48:49]
	v_pk_add_f32 v[14:15], v[14:15], v[50:51]
	v_pk_add_f32 v[16:17], v[16:17], v[52:53]
	v_pk_add_f32 v[18:19], v[18:19], v[54:55]
	v_pk_add_f32 v[20:21], v[20:21], v[56:57]
	v_pk_add_f32 v[22:23], v[22:23], v[58:59]
	s_waitcnt vmcnt(4)
	v_pk_add_f32 v[8:9], v[8:9], v[62:63]
	v_pk_add_f32 v[10:11], v[10:11], v[64:65]
	v_pk_add_f32 v[12:13], v[12:13], v[66:67]
	v_pk_add_f32 v[14:15], v[14:15], v[68:69]
	v_pk_add_f32 v[16:17], v[16:17], v[70:71]
	v_pk_add_f32 v[18:19], v[18:19], v[72:73]
	v_pk_add_f32 v[20:21], v[20:21], v[74:75]
	v_pk_add_f32 v[22:23], v[22:23], v[76:77]
	s_waitcnt vmcnt(0)
	v_pk_add_f32 v[8:9], v[8:9], v[82:83]
	v_pk_add_f32 v[10:11], v[10:11], v[84:85]
	v_pk_add_f32 v[12:13], v[12:13], v[86:87]
	v_pk_add_f32 v[14:15], v[14:15], v[88:89]
	v_pk_add_f32 v[16:17], v[16:17], v[90:91]
	v_pk_add_f32 v[18:19], v[18:19], v[92:93]
	v_pk_add_f32 v[20:21], v[20:21], v[94:95]
	v_pk_add_f32 v[22:23], v[22:23], v[96:97]
	s_add_i32 s27, s27, -1
	s_cmp_lg_u32 s27, 0
	s_cbranch_scc1 .Lslab_loop_bn
	v_readlane_b32 s26, v250, 15
	v_readlane_b32 s27, v250, 16
	s_add_u32 s18, s26, 0xb506000
	s_addc_u32 s19, s27, 0
	v_lshl_add_u64 v[4:5], s[18:19], 0, v[2:3]
	global_store_dwordx4 v[4:5], v[8:11], off
	global_store_dwordx4 v[4:5], v[12:15], off offset:1024
	global_store_dwordx4 v[4:5], v[16:19], off offset:2048
	global_store_dwordx4 v[4:5], v[20:23], off offset:3072
	s_branch .Lslab_done_b
.Lslab_b_l0:
	v_readlane_b32 s26, v250, 15
	v_readlane_b32 s27, v250, 16
	s_add_u32 s18, s26, 0xb506000
	s_addc_u32 s19, s27, 0
	v_lshl_add_u64 v[4:5], s[18:19], 0, v[2:3]
	global_load_dwordx4 v[8:11], v[4:5], off sc1
	global_load_dwordx4 v[12:15], v[4:5], off offset:1024 sc1
	global_load_dwordx4 v[16:19], v[4:5], off offset:2048 sc1
	global_load_dwordx4 v[20:23], v[4:5], off offset:3072 sc1
	v_readlane_b32 s26, v250, 15
	v_readlane_b32 s27, v250, 16
	s_add_u32 s18, s26, 0x284e6000
	s_addc_u32 s19, s27, 0
	global_load_dword v6, v3, s[18:19] sc1
	v_readlane_b32 s26, v250, 15
	v_readlane_b32 s27, v250, 16
	s_add_u32 s18, s26, 0x274e6000
	s_addc_u32 s19, s27, 0
	v_lshl_add_u64 v[24:25], s[18:19], 0, v[2:3]
	s_mov_b64 s[18:19], 0x100000
	v_lshl_add_u64 v[26:27], v[24:25], 0, s[18:19]
	v_lshl_add_u64 v[78:79], v[26:27], 0, s[18:19]
	v_lshl_add_u64 v[98:99], v[78:79], 0, s[18:19]
	s_mov_b64 s[18:19], 0x400000
	s_waitcnt vmcnt(0)
	v_readfirstlane_b32 s27, v6
	s_lshr_b32 s27, s27, 2
.Lslab_loop_br1:
	global_load_dwordx4 v[28:31], v[24:25], off
	global_load_dwordx4 v[32:35], v[24:25], off offset:1024
	global_load_dwordx4 v[36:39], v[24:25], off offset:2048
	global_load_dwordx4 v[40:43], v[24:25], off offset:3072
	global_load_dwordx4 v[44:47], v[26:27], off
	global_load_dwordx4 v[48:51], v[26:27], off offset:1024
	global_load_dwordx4 v[52:55], v[26:27], off offset:2048
	global_load_dwordx4 v[56:59], v[26:27], off offset:3072
	global_load_dwordx4 v[62:65], v[78:79], off
	global_load_dwordx4 v[66:69], v[78:79], off offset:1024
	global_load_dwordx4 v[70:73], v[78:79], off offset:2048
	global_load_dwordx4 v[74:77], v[78:79], off offset:3072
	global_load_dwordx4 v[82:85], v[98:99], off
	global_load_dwordx4 v[86:89], v[98:99], off offset:1024
	global_load_dwordx4 v[90:93], v[98:99], off offset:2048
	global_load_dwordx4 v[94:97], v[98:99], off offset:3072
	v_lshl_add_u64 v[24:25], v[24:25], 0, s[18:19]
	v_lshl_add_u64 v[26:27], v[26:27], 0, s[18:19]
	v_lshl_add_u64 v[78:79], v[78:79], 0, s[18:19]
	v_lshl_add_u64 v[98:99], v[98:99], 0, s[18:19]
	s_waitcnt vmcnt(12)
	v_pk_add_f32 v[8:9], v[8:9], v[28:29]
	v_pk_add_f32 v[10:11], v[10:11], v[30:31]
	v_pk_add_f32 v[12:13], v[12:13], v[32:33]
	v_pk_add_f32 v[14:15], v[14:15], v[34:35]
	v_pk_add_f32 v[16:17], v[16:17], v[36:37]
	v_pk_add_f32 v[18:19], v[18:19], v[38:39]
	v_pk_add_f32 v[20:21], v[20:21], v[40:41]
	v_pk_add_f32 v[22:23], v[22:23], v[42:43]
	s_waitcnt vmcnt(8)
	v_pk_add_f32 v[8:9], v[8:9], v[44:45]
	v_pk_add_f32 v[10:11], v[10:11], v[46:47]
	v_pk_add_f32 v[12:13], v[12:13], v[48:49]
	v_pk_add_f32 v[14:15], v[14:15], v[50:51]
	v_pk_add_f32 v[16:17], v[16:17], v[52:53]
	v_pk_add_f32 v[18:19], v[18:19], v[54:55]
	v_pk_add_f32 v[20:21], v[20:21], v[56:57]
	v_pk_add_f32 v[22:23], v[22:23], v[58:59]
	s_waitcnt vmcnt(4)
	v_pk_add_f32 v[8:9], v[8:9], v[62:63]
	v_pk_add_f32 v[10:11], v[10:11], v[64:65]
	v_pk_add_f32 v[12:13], v[12:13], v[66:67]
	v_pk_add_f32 v[14:15], v[14:15], v[68:69]
	v_pk_add_f32 v[16:17], v[16:17], v[70:71]
	v_pk_add_f32 v[18:19], v[18:19], v[72:73]
	v_pk_add_f32 v[20:21], v[20:21], v[74:75]
	v_pk_add_f32 v[22:23], v[22:23], v[76:77]
	s_waitcnt vmcnt(0)
	v_pk_add_f32 v[8:9], v[8:9], v[82:83]
	v_pk_add_f32 v[10:11], v[10:11], v[84:85]
	v_pk_add_f32 v[12:13], v[12:13], v[86:87]
	v_pk_add_f32 v[14:15], v[14:15], v[88:89]
	v_pk_add_f32 v[16:17], v[16:17], v[90:91]
	v_pk_add_f32 v[18:19], v[18:19], v[92:93]
	v_pk_add_f32 v[20:21], v[20:21], v[94:95]
	v_pk_add_f32 v[22:23], v[22:23], v[96:97]
	s_add_i32 s27, s27, -1
	s_cmp_lg_u32 s27, 0
	s_cbranch_scc1 .Lslab_loop_br1
	v_readlane_b32 s26, v250, 13
	v_readlane_b32 s27, v250, 14
	s_add_u32 s18, s26, 0x1000
	s_addc_u32 s19, s27, 0
	v_lshl_add_u64 v[4:5], s[18:19], 0, v[60:61]
	global_store_dwordx4 v[4:5], v[8:11], off
	global_store_dwordx4 v[4:5], v[12:15], off offset:1024
	global_store_dwordx4 v[4:5], v[16:19], off offset:2048
	global_store_dwordx4 v[4:5], v[20:23], off offset:3072
	v_readlane_b32 s26, v250, 6
	s_cmp_gt_u32 s26, 0x7f
	s_cbranch_scc1 .Lslab_done_b
	s_cmp_eq_u32 s26, 0
	s_cbranch_scc1 .Lslab_b_row0plain
	v_readlane_b32 s26, v250, 15
	v_readlane_b32 s27, v250, 16
	s_add_u32 s18, s26, 0xb505000
	s_addc_u32 s19, s27, 0
	v_lshl_add_u64 v[4:5], s[18:19], 0, v[2:3]
	global_load_dwordx4 v[8:11], v[4:5], off sc1
	global_load_dwordx4 v[12:15], v[4:5], off offset:1024 sc1
	global_load_dwordx4 v[16:19], v[4:5], off offset:2048 sc1
	global_load_dwordx4 v[20:23], v[4:5], off offset:3072 sc1
	v_readlane_b32 s26, v250, 15
	v_readlane_b32 s27, v250, 16
	s_add_u32 s18, s26, 0x284e6000
	s_addc_u32 s19, s27, 0
	global_load_dword v6, v3, s[18:19] sc1
	v_readlane_b32 s26, v250, 15
	v_readlane_b32 s27, v250, 16
	s_add_u32 s18, s26, 0x274e5000
	s_addc_u32 s19, s27, 0
	v_lshl_add_u64 v[24:25], s[18:19], 0, v[2:3]
	s_mov_b64 s[18:19], 0x100000
	v_lshl_add_u64 v[26:27], v[24:25], 0, s[18:19]
	v_lshl_add_u64 v[78:79], v[26:27], 0, s[18:19]
	v_lshl_add_u64 v[98:99], v[78:79], 0, s[18:19]
	s_mov_b64 s[18:19], 0x400000
	s_waitcnt vmcnt(0)
	v_readfirstlane_b32 s27, v6
	s_lshr_b32 s27, s27, 2
.Lslab_loop_br0:
	global_load_dwordx4 v[28:31], v[24:25], off
	global_load_dwordx4 v[32:35], v[24:25], off offset:1024
	global_load_dwordx4 v[36:39], v[24:25], off offset:2048
	global_load_dwordx4 v[40:43], v[24:25], off offset:3072
	global_load_dwordx4 v[44:47], v[26:27], off
	global_load_dwordx4 v[48:51], v[26:27], off offset:1024
	global_load_dwordx4 v[52:55], v[26:27], off offset:2048
	global_load_dwordx4 v[56:59], v[26:27], off offset:3072
	global_load_dwordx4 v[62:65], v[78:79], off
	global_load_dwordx4 v[66:69], v[78:79], off offset:1024
	global_load_dwordx4 v[70:73], v[78:79], off offset:2048
	global_load_dwordx4 v[74:77], v[78:79], off offset:3072
	global_load_dwordx4 v[82:85], v[98:99], off
	global_load_dwordx4 v[86:89], v[98:99], off offset:1024
	global_load_dwordx4 v[90:93], v[98:99], off offset:2048
	global_load_dwordx4 v[94:97], v[98:99], off offset:3072
	v_lshl_add_u64 v[24:25], v[24:25], 0, s[18:19]
	v_lshl_add_u64 v[26:27], v[26:27], 0, s[18:19]
	v_lshl_add_u64 v[78:79], v[78:79], 0, s[18:19]
	v_lshl_add_u64 v[98:99], v[98:99], 0, s[18:19]
	s_waitcnt vmcnt(12)
	v_pk_add_f32 v[8:9], v[8:9], v[28:29]
	v_pk_add_f32 v[10:11], v[10:11], v[30:31]
	v_pk_add_f32 v[12:13], v[12:13], v[32:33]
	v_pk_add_f32 v[14:15], v[14:15], v[34:35]
	v_pk_add_f32 v[16:17], v[16:17], v[36:37]
	v_pk_add_f32 v[18:19], v[18:19], v[38:39]
	v_pk_add_f32 v[20:21], v[20:21], v[40:41]
	v_pk_add_f32 v[22:23], v[22:23], v[42:43]
	s_waitcnt vmcnt(8)
	v_pk_add_f32 v[8:9], v[8:9], v[44:45]
	v_pk_add_f32 v[10:11], v[10:11], v[46:47]
	v_pk_add_f32 v[12:13], v[12:13], v[48:49]
	v_pk_add_f32 v[14:15], v[14:15], v[50:51]
	v_pk_add_f32 v[16:17], v[16:17], v[52:53]
	v_pk_add_f32 v[18:19], v[18:19], v[54:55]
	v_pk_add_f32 v[20:21], v[20:21], v[56:57]
	v_pk_add_f32 v[22:23], v[22:23], v[58:59]
	s_waitcnt vmcnt(4)
	v_pk_add_f32 v[8:9], v[8:9], v[62:63]
	v_pk_add_f32 v[10:11], v[10:11], v[64:65]
	v_pk_add_f32 v[12:13], v[12:13], v[66:67]
	v_pk_add_f32 v[14:15], v[14:15], v[68:69]
	v_pk_add_f32 v[16:17], v[16:17], v[70:71]
	v_pk_add_f32 v[18:19], v[18:19], v[72:73]
	v_pk_add_f32 v[20:21], v[20:21], v[74:75]
	v_pk_add_f32 v[22:23], v[22:23], v[76:77]
	s_waitcnt vmcnt(0)
	v_pk_add_f32 v[8:9], v[8:9], v[82:83]
	v_pk_add_f32 v[10:11], v[10:11], v[84:85]
	v_pk_add_f32 v[12:13], v[12:13], v[86:87]
	v_pk_add_f32 v[14:15], v[14:15], v[88:89]
	v_pk_add_f32 v[16:17], v[16:17], v[90:91]
	v_pk_add_f32 v[18:19], v[18:19], v[92:93]
	v_pk_add_f32 v[20:21], v[20:21], v[94:95]
	v_pk_add_f32 v[22:23], v[22:23], v[96:97]
	s_add_i32 s27, s27, -1
	s_cmp_lg_u32 s27, 0
	s_cbranch_scc1 .Lslab_loop_br0
	v_readlane_b32 s26, v250, 13
	v_readlane_b32 s27, v250, 14
	s_add_u32 s18, s26, 0x0
	s_addc_u32 s19, s27, 0
	v_lshl_add_u64 v[4:5], s[18:19], 0, v[60:61]
	global_store_dwordx4 v[4:5], v[8:11], off
	global_store_dwordx4 v[4:5], v[12:15], off offset:1024
	global_store_dwordx4 v[4:5], v[16:19], off offset:2048
	global_store_dwordx4 v[4:5], v[20:23], off offset:3072
	s_branch .Lslab_done_b
